# GEMM epilogues: xor-16/xor-32 row reductions with v_permlane16/32_swap instead of ds_bpermute round trips (86 sites)
# speedup vs baseline: 1.0132x; 1.0054x over previous
.LBB0_248:
	v_and_b32_e32 v131, 64, v197
	v_xor_b32_e32 v130, 16, v197
	v_add_u32_e32 v131, 64, v131
	v_cmp_lt_i32_e32 vcc, v130, v131
	s_lshl_b32 s92, s31, 8
	v_add_u32_e32 v146, s35, v128
	v_cndmask_b32_e32 v130, v197, v130, vcc
	v_lshlrev_b32_e32 v147, 2, v130
	v_xor_b32_e32 v130, 32, v197
	v_add_u32_e32 v158, s92, v146
	v_lshlrev_b32_e32 v128, 2, v134
	v_cmp_lt_i32_e32 vcc, v130, v131
	v_ashrrev_i32_e32 v129, 31, v128
	v_ashrrev_i32_e32 v159, 31, v158
	v_cndmask_b32_e32 v130, v197, v130, vcc
	v_lshl_add_u64 v[128:129], v[128:129], 2, s[60:61]
	v_lshlrev_b32_e32 v135, 2, v130
	v_lshlrev_b64 v[130:131], 6, v[158:159]
	v_lshl_add_u64 v[130:131], v[128:129], 0, v[130:131]
	global_load_dwordx4 v[176:179], v[130:131], off offset:1024
	global_load_dwordx4 v[180:183], v[130:131], off offset:2048
	global_load_dwordx4 v[184:187], v[130:131], off offset:3072
	v_add_co_u32_e32 v226, vcc, 0x2000, v130
	s_nop 1
	v_addc_co_u32_e32 v227, vcc, 0, v131, vcc
	global_load_dwordx4 v[188:191], v[226:227], off
	global_load_dwordx4 v[198:201], v[226:227], off offset:1024
	global_load_dwordx4 v[218:221], v[226:227], off offset:2048
	global_load_dwordx4 v[222:225], v[226:227], off offset:3072
	global_load_dwordx4 v[130:133], v[130:131], off
	s_waitcnt vmcnt(0)
	v_mov_b32_e32 v148, v131
	v_mov_b32_e32 v149, v132
	v_mov_b32_e32 v131, v133
	v_pk_add_f32 v[148:149], v[148:149], v[130:131]
	v_add_u32_e32 v130, 16, v158
	v_ashrrev_i32_e32 v131, 31, v130
	v_lshlrev_b64 v[130:131], 6, v[130:131]
	v_lshl_add_u64 v[130:131], v[128:129], 0, v[130:131]
	v_mov_b32_e32 v130, v176
	v_mov_b32_e32 v131, v177
	v_mov_b32_e32 v132, v178
	v_mov_b32_e32 v133, v179
	v_mov_b32_e32 v150, v131
	v_mov_b32_e32 v151, v132
	v_mov_b32_e32 v131, v133
	v_pk_add_f32 v[130:131], v[150:151], v[130:131]
	v_mov_b32_e32 v133, v148
	v_mov_b32_e32 v132, v130
	v_mov_b32_e32 v148, v131
	v_pk_add_f32 v[130:131], v[132:133], v[148:149]
	v_mov_b32_e32 v133, v131
	s_nop 1
	v_permlane16_swap_b32_e32 v133, v131
	v_mov_b32_e32 v132, v130
	s_nop 1
	v_permlane16_swap_b32_e32 v132, v130
	s_waitcnt lgkmcnt(0)
	v_pk_add_f32 v[130:131], v[130:131], v[132:133]
	v_mov_b32_e32 v133, v131
	s_nop 1
	v_permlane32_swap_b32_e32 v133, v131
	v_mov_b32_e32 v132, v130
	s_nop 1
	v_permlane32_swap_b32_e32 v132, v130
	s_waitcnt lgkmcnt(0)
	v_pk_add_f32 v[130:131], v[130:131], v[132:133]
	s_nop 0
	v_pk_fma_f32 v[164:165], v[130:131], s[66:67], v[196:197] op_sel_hi:[1,0,0]
	s_nop 0
	v_mul_f32_e32 v130, 0x4b800000, v165
	v_cmp_gt_f32_e32 vcc, s80, v165
	v_cmp_gt_f32_e64 s[0:1], s80, v164
	s_nop 0
	v_cndmask_b32_e32 v130, v165, v130, vcc
	v_rsq_f32_e32 v130, v130
	s_nop 0
	v_mul_f32_e32 v131, 0x45800000, v130
	v_cndmask_b32_e32 v166, v130, v131, vcc
	v_add_u32_e32 v130, 32, v158
	v_ashrrev_i32_e32 v131, 31, v130
	v_lshlrev_b64 v[130:131], 6, v[130:131]
	v_lshl_add_u64 v[130:131], v[128:129], 0, v[130:131]
	v_mov_b32_e32 v130, v180
	v_mov_b32_e32 v131, v181
	v_mov_b32_e32 v132, v182
	v_mov_b32_e32 v133, v183
	s_add_i32 vcc_lo, s30, -6
	s_cmp_gt_u32 vcc_lo, 7
	s_cselect_b64 s[30:31], -1, 0
	s_ashr_i32 s7, s6, 31
	s_lshl_b64 s[6:7], s[6:7], 1
	s_add_u32 s48, s4, s6
	s_addc_u32 s49, s5, s7
	s_cmp_lg_u64 s[96:97], 0
	s_cselect_b64 s[28:29], -1, 0
	s_xor_b64 s[6:7], s[88:89], -1
	s_and_b64 s[88:89], s[6:7], s[28:29]
	s_mov_b64 s[4:5], -1
	s_cmp_lt_u32 vcc_lo, 8
	v_mov_b32_e32 v148, v131
	v_mov_b32_e32 v149, v132
	v_mov_b32_e32 v131, v133
	v_pk_add_f32 v[148:149], v[148:149], v[130:131]
	v_add_u32_e32 v130, 48, v158
	v_ashrrev_i32_e32 v131, 31, v130
	v_lshlrev_b64 v[130:131], 6, v[130:131]
	v_lshl_add_u64 v[130:131], v[128:129], 0, v[130:131]
	v_mov_b32_e32 v130, v184
	v_mov_b32_e32 v131, v185
	v_mov_b32_e32 v132, v186
	v_mov_b32_e32 v133, v187
	v_mov_b32_e32 v150, v131
	v_mov_b32_e32 v151, v132
	v_mov_b32_e32 v131, v133
	v_pk_add_f32 v[130:131], v[150:151], v[130:131]
	v_mov_b32_e32 v133, v148
	v_mov_b32_e32 v132, v130
	v_mov_b32_e32 v148, v131
	v_pk_add_f32 v[130:131], v[132:133], v[148:149]
	v_mov_b32_e32 v133, v131
	s_nop 1
	v_permlane16_swap_b32_e32 v133, v131
	v_mov_b32_e32 v132, v130
	s_nop 1
	v_permlane16_swap_b32_e32 v132, v130
	s_waitcnt lgkmcnt(0)
	v_pk_add_f32 v[160:161], v[130:131], v[132:133]
	v_add_u32_e32 v130, 0x80, v158
	v_ashrrev_i32_e32 v131, 31, v130
	v_lshlrev_b64 v[130:131], 6, v[130:131]
	v_lshl_add_u64 v[130:131], v[128:129], 0, v[130:131]
	v_mov_b32_e32 v130, v188
	v_mov_b32_e32 v131, v189
	v_mov_b32_e32 v132, v190
	v_mov_b32_e32 v133, v191
	ds_bpermute_b32 v163, v135, v161
	ds_bpermute_b32 v162, v135, v160
	v_mov_b32_e32 v148, v131
	v_mov_b32_e32 v149, v132
	v_mov_b32_e32 v131, v133
	v_pk_add_f32 v[148:149], v[148:149], v[130:131]
	v_add_u32_e32 v130, 0x90, v158
	v_ashrrev_i32_e32 v131, 31, v130
	v_lshlrev_b64 v[130:131], 6, v[130:131]
	v_lshl_add_u64 v[130:131], v[128:129], 0, v[130:131]
	v_mov_b32_e32 v130, v198
	v_mov_b32_e32 v131, v199
	v_mov_b32_e32 v132, v200
	v_mov_b32_e32 v133, v201
	v_mov_b32_e32 v150, v131
	v_mov_b32_e32 v151, v132
	v_mov_b32_e32 v131, v133
	v_pk_add_f32 v[130:131], v[150:151], v[130:131]
	v_mov_b32_e32 v133, v148
	v_mov_b32_e32 v132, v130
	v_mov_b32_e32 v148, v131
	v_pk_add_f32 v[130:131], v[132:133], v[148:149]
	v_mov_b32_e32 v133, v131
	s_nop 1
	v_permlane16_swap_b32_e32 v133, v131
	v_mov_b32_e32 v132, v130
	s_nop 1
	v_permlane16_swap_b32_e32 v132, v130
	s_waitcnt lgkmcnt(0)
	v_pk_add_f32 v[150:151], v[130:131], v[132:133]
	v_add_u32_e32 v130, 0xa0, v158
	v_ashrrev_i32_e32 v131, 31, v130
	v_lshlrev_b64 v[130:131], 6, v[130:131]
	v_lshl_add_u64 v[130:131], v[128:129], 0, v[130:131]
	v_mov_b32_e32 v130, v218
	v_mov_b32_e32 v131, v219
	v_mov_b32_e32 v132, v220
	v_mov_b32_e32 v133, v221
	ds_bpermute_b32 v153, v135, v151
	ds_bpermute_b32 v152, v135, v150
	v_mov_b32_e32 v148, v131
	v_mov_b32_e32 v149, v132
	v_mov_b32_e32 v131, v133
	v_pk_add_f32 v[132:133], v[148:149], v[130:131]
	v_add_u32_e32 v130, 0xb0, v158
	v_ashrrev_i32_e32 v131, 31, v130
	v_lshlrev_b64 v[130:131], 6, v[130:131]
	v_lshl_add_u64 v[128:129], v[128:129], 0, v[130:131]
	v_mov_b32_e32 v128, v222
	v_mov_b32_e32 v129, v223
	v_mov_b32_e32 v130, v224
	v_mov_b32_e32 v131, v225
	v_mov_b32_e32 v148, v129
	v_mov_b32_e32 v149, v130
	v_mov_b32_e32 v129, v131
	v_pk_add_f32 v[128:129], v[148:149], v[128:129]
	v_mov_b32_e32 v131, v132
	v_mov_b32_e32 v130, v128
	v_mov_b32_e32 v132, v129
	v_pk_add_f32 v[128:129], v[130:131], v[132:133]
	v_mov_b32_e32 v131, v129
	s_nop 1
	v_permlane16_swap_b32_e32 v131, v129
	v_mov_b32_e32 v130, v128
	s_nop 1
	v_permlane16_swap_b32_e32 v130, v128
	v_lshl_add_u32 v148, v134, 3, s26
	v_ashrrev_i32_e32 v149, 31, v148
	s_waitcnt lgkmcnt(0)
	v_pk_add_f32 v[154:155], v[128:129], v[130:131]
	ds_bpermute_b32 v157, v135, v155
	ds_bpermute_b32 v156, v135, v154
	s_cbranch_scc1 .LBB0_254
	v_mul_lo_u32 v130, s25, v158
	v_mul_lo_u32 v131, s24, v159
	v_mad_u64_u32 v[128:129], s[4:5], s24, v158, 0
	v_add3_u32 v129, v129, v131, v130
	v_ashrrev_i32_e32 v147, 31, v146
	v_lshl_add_u64 v[168:169], v[128:129], 1, s[48:49]
	v_lshlrev_b64 v[128:129], 10, v[146:147]
	v_lshl_add_u64 v[180:181], s[96:97], 0, v[128:129]
	v_pk_mul_f32 v[130:131], v[122:123], v[166:167] op_sel_hi:[1,0]
	v_pk_mul_f32 v[128:129], v[120:121], v[166:167] op_sel_hi:[1,0]
	v_pk_mul_f32 v[134:135], v[118:119], v[166:167] op_sel_hi:[1,0]
	v_pk_mul_f32 v[132:133], v[116:117], v[166:167] op_sel_hi:[1,0]
	v_cvt_pk_bf16_f32 v176, v128, v129
	v_cvt_pk_bf16_f32 v177, v130, v131
	v_cvt_pk_bf16_f32 v178, v132, v133
	v_cvt_pk_bf16_f32 v179, v134, v135
	v_lshl_add_u64 v[170:171], v[148:149], 1, v[168:169]
	s_and_b64 vcc, exec, s[88:89]
	v_lshl_add_u64 v[168:169], v[148:149], 2, v[180:181]
	global_store_dwordx4 v[170:171], v[176:179], off
	s_cbranch_vccz .LBB0_251
	global_store_dwordx4 v[168:169], v[128:131], off
	global_store_dwordx4 v[168:169], v[132:135], off offset:16

.LBB0_684:
	s_lshl_b32 s24, s55, 8
	v_mov_b32_e32 v128, v184
	v_mov_b32_e32 v129, v185
	s_or_b32 s24, s24, s42
	v_and_b32_e32 v130, 64, v197
	v_lshl_add_u32 v166, v128, 3, s24
	s_lshl_b32 s24, s72, 8
	s_add_i32 s24, s24, s35
	v_add_u32_e32 v168, s24, v129
	v_xor_b32_e32 v129, 16, v197
	v_add_u32_e32 v130, 64, v130
	v_cmp_lt_i32_e32 vcc, v129, v130
	v_ashrrev_i32_e32 v167, 31, v166
	v_lshlrev_b64 v[190:191], 1, v[166:167]
	v_cndmask_b32_e32 v129, v197, v129, vcc
	v_lshlrev_b32_e32 v189, 2, v129
	v_xor_b32_e32 v129, 32, v197
	v_cmp_lt_i32_e32 vcc, v129, v130
	v_ashrrev_i32_e32 v169, 31, v168
	v_lshl_add_u64 v[170:171], s[36:37], 0, v[190:191]
	v_cndmask_b32_e32 v129, v197, v129, vcc
	v_lshlrev_b64 v[218:219], 11, v[168:169]
	v_lshlrev_b32_e32 v188, 2, v129
	v_cmp_eq_u32_e32 vcc, 0, v128
	v_lshl_add_u64 v[128:129], v[170:171], 0, v[218:219]
	global_load_dwordx4 v[198:201], v[128:129], off
	global_load_dwordx4 v[152:155], v[128:129], off offset:256
	v_add_u32_e32 v180, 16, v168
	v_ashrrev_i32_e32 v181, 31, v180
	v_add_u32_e32 v176, 32, v168
	v_lshlrev_b64 v[182:183], 11, v[180:181]
	v_ashrrev_i32_e32 v177, 31, v176
	v_add_u32_e32 v172, 48, v168
	v_lshl_add_u64 v[128:129], v[170:171], 0, v[182:183]
	v_lshlrev_b64 v[178:179], 11, v[176:177]
	v_ashrrev_i32_e32 v173, 31, v172
	global_load_dwordx4 v[148:151], v[128:129], off
	global_load_dwordx4 v[144:147], v[128:129], off offset:256
	v_lshl_add_u64 v[128:129], v[170:171], 0, v[178:179]
	v_lshlrev_b64 v[174:175], 11, v[172:173]
	global_load_dwordx4 v[140:143], v[128:129], off
	global_load_dwordx4 v[136:139], v[128:129], off offset:256
	v_lshl_add_u64 v[128:129], v[170:171], 0, v[174:175]
	global_load_dwordx4 v[132:135], v[128:129], off
	s_nop 0
	global_load_dwordx4 v[128:131], v[128:129], off offset:256
	s_lshl_b32 s24, s55, 2
	s_ashr_i32 s25, s24, 31
	s_waitcnt vmcnt(0)
	v_lshlrev_b32_e32 v220, 16, v198
	v_and_b32_e32 v221, 0xffff0000, v198
	v_lshlrev_b32_e32 v198, 16, v199
	v_and_b32_e32 v199, 0xffff0000, v199
	v_lshlrev_b32_e32 v222, 16, v200
	v_and_b32_e32 v223, 0xffff0000, v200
	v_lshlrev_b32_e32 v200, 16, v201
	v_and_b32_e32 v201, 0xffff0000, v201
	v_pk_add_f32 v[198:199], v[122:123], v[198:199]
	v_pk_add_f32 v[220:221], v[120:121], v[220:221]
	v_pk_add_f32 v[126:127], v[126:127], v[200:201]
	v_pk_add_f32 v[124:125], v[124:125], v[222:223]
	v_lshl_add_u64 v[200:201], s[36:37], 0, v[218:219]
	v_cvt_pk_bf16_f32 v120, v220, v221
	v_cvt_pk_bf16_f32 v121, v198, v199
	v_cvt_pk_bf16_f32 v122, v124, v125
	v_cvt_pk_bf16_f32 v123, v126, v127
	v_lshl_add_u64 v[190:191], v[200:201], 0, v[190:191]
	global_store_dwordx4 v[190:191], v[120:123], off
	s_nop 1
	v_mul_f32_e32 v120, v221, v221
	v_mul_f32_e32 v121, v199, v199
	v_fmac_f32_e32 v120, v220, v220
	v_fmac_f32_e32 v121, v198, v198
	v_add_f32_e32 v120, v120, v121
	v_mul_f32_e32 v121, v125, v125
	v_fmac_f32_e32 v121, v124, v124
	v_add_f32_e32 v120, v121, v120
	v_mul_f32_e32 v121, v127, v127
	v_fmac_f32_e32 v121, v126, v126
	v_add_f32_e32 v192, v121, v120
	v_lshlrev_b32_e32 v120, 16, v152
	v_and_b32_e32 v121, 0xffff0000, v152
	v_lshlrev_b32_e32 v122, 16, v153
	v_and_b32_e32 v123, 0xffff0000, v153
	v_lshlrev_b32_e32 v124, 16, v154
	v_and_b32_e32 v125, 0xffff0000, v154
	v_lshlrev_b32_e32 v126, 16, v155
	v_and_b32_e32 v127, 0xffff0000, v155
	v_pk_add_f32 v[118:119], v[118:119], v[122:123]
	v_pk_add_f32 v[116:117], v[116:117], v[120:121]
	v_pk_add_f32 v[120:121], v[114:115], v[126:127]
	v_pk_add_f32 v[122:123], v[112:113], v[124:125]
	v_cvt_pk_bf16_f32 v112, v116, v117
	v_cvt_pk_bf16_f32 v113, v118, v119
	v_cvt_pk_bf16_f32 v114, v122, v123
	v_cvt_pk_bf16_f32 v115, v120, v121
	global_store_dwordx4 v[190:191], v[112:115], off offset:256
	s_nop 1
	v_mul_f32_e32 v112, v117, v117
	v_mul_f32_e32 v113, v119, v119
	v_fmac_f32_e32 v112, v116, v116
	v_fmac_f32_e32 v113, v118, v118
	v_add_f32_e32 v112, v112, v113
	v_mul_f32_e32 v113, v123, v123
	v_fmac_f32_e32 v113, v122, v122
	v_add_f32_e32 v112, v113, v112
	v_mul_f32_e32 v113, v121, v121
	v_fmac_f32_e32 v113, v120, v120
	v_add_f32_e32 v112, v113, v112
	v_add_f32_e32 v112, v192, v112
	v_mov_b32_e32 v113, v112
	s_nop 1
	v_permlane16_swap_b32_e32 v113, v112
	s_waitcnt lgkmcnt(0)
	v_add_f32_e32 v112, v112, v113
	v_mov_b32_e32 v113, v112
	s_nop 1
	v_permlane32_swap_b32_e32 v113, v112
	s_and_saveexec_b64 s[28:29], vcc
	s_cbranch_execz .LBB0_686
	s_waitcnt lgkmcnt(0)
	v_add_f32_e32 v114, v112, v113
	v_lshlrev_b64 v[112:113], 6, v[168:169]
	v_lshl_add_u64 v[112:113], s[12:13], 0, v[112:113]
	v_lshl_add_u64 v[112:113], s[24:25], 2, v[112:113]
	s_lshl_b32 s92, s31, 2
	v_lshl_add_u64 v[112:113], v[112:113], 0, s[92:93]
	global_store_dword v[112:113], v114, off
.LBB0_686:
	s_or_b64 exec, exec, s[28:29]
	v_lshlrev_b32_e32 v112, 16, v148
	s_waitcnt lgkmcnt(0)
	v_and_b32_e32 v113, 0xffff0000, v148
	v_lshlrev_b32_e32 v114, 16, v149
	v_and_b32_e32 v115, 0xffff0000, v149
	v_lshlrev_b32_e32 v116, 16, v150
	v_and_b32_e32 v117, 0xffff0000, v150
	v_pk_add_f32 v[108:109], v[108:109], v[112:113]
	v_pk_add_f32 v[110:111], v[110:111], v[114:115]
	v_pk_add_f32 v[114:115], v[104:105], v[116:117]
	v_cvt_pk_bf16_f32 v104, v108, v109
	v_mul_f32_e32 v109, v109, v109
	v_fmac_f32_e32 v109, v108, v108
	v_mul_f32_e32 v108, v111, v111
	v_fmac_f32_e32 v108, v110, v110
	v_lshlrev_b32_e32 v118, 16, v151
	v_and_b32_e32 v119, 0xffff0000, v151
	v_add_f32_e32 v108, v109, v108
	v_mul_f32_e32 v109, v115, v115
	v_pk_add_f32 v[112:113], v[106:107], v[118:119]
	v_fmac_f32_e32 v109, v114, v114
	v_add_f32_e32 v108, v109, v108
	v_mul_f32_e32 v109, v113, v113
	v_fmac_f32_e32 v109, v112, v112
	v_cvt_pk_bf16_f32 v105, v110, v111
	v_add_f32_e32 v116, v109, v108
	v_lshlrev_b32_e32 v108, 16, v144
	v_and_b32_e32 v109, 0xffff0000, v144
	v_lshlrev_b32_e32 v110, 16, v145
	v_and_b32_e32 v111, 0xffff0000, v145
	v_cvt_pk_bf16_f32 v107, v112, v113
	v_lshlrev_b32_e32 v112, 16, v146
	v_and_b32_e32 v113, 0xffff0000, v146
	v_pk_add_f32 v[102:103], v[102:103], v[110:111]
	v_pk_add_f32 v[100:101], v[100:101], v[108:109]
	v_pk_add_f32 v[110:111], v[96:97], v[112:113]
	v_mul_f32_e32 v96, v101, v101
	v_mul_f32_e32 v97, v103, v103
	v_fmac_f32_e32 v96, v100, v100
	v_fmac_f32_e32 v97, v102, v102
	v_cvt_pk_bf16_f32 v106, v114, v115
	v_lshlrev_b32_e32 v114, 16, v147
	v_and_b32_e32 v115, 0xffff0000, v147
	v_add_f32_e32 v96, v96, v97
	v_mul_f32_e32 v97, v111, v111
	v_pk_add_f32 v[108:109], v[98:99], v[114:115]
	v_fmac_f32_e32 v97, v110, v110
	v_add_f32_e32 v96, v97, v96
	v_mul_f32_e32 v97, v109, v109
	v_fmac_f32_e32 v97, v108, v108
	v_add_f32_e32 v96, v97, v96
	v_add_f32_e32 v99, v116, v96
	v_mov_b32_e32 v114, v99
	s_nop 1
	v_permlane16_swap_b32_e32 v114, v99
	v_lshl_add_u64 v[96:97], s[36:37], 0, v[182:183]
	v_lshl_add_u64 v[112:113], v[166:167], 1, v[96:97]
	v_cvt_pk_bf16_f32 v98, v100, v101
	v_cvt_pk_bf16_f32 v100, v110, v111
	s_waitcnt lgkmcnt(0)
	v_add_f32_e32 v96, v99, v114
	v_mov_b32_e32 v97, v96
	s_nop 1
	v_permlane32_swap_b32_e32 v97, v96
	v_cvt_pk_bf16_f32 v99, v102, v103
	v_cvt_pk_bf16_f32 v101, v108, v109
	global_store_dwordx4 v[112:113], v[104:107], off
	global_store_dwordx4 v[112:113], v[98:101], off offset:256
	s_and_saveexec_b64 s[28:29], vcc
	s_cbranch_execz .LBB0_688
	s_waitcnt lgkmcnt(0)
	v_add_f32_e32 v98, v96, v97
	v_lshlrev_b64 v[96:97], 6, v[180:181]
	v_lshl_add_u64 v[96:97], s[12:13], 0, v[96:97]
	v_lshl_add_u64 v[96:97], s[24:25], 2, v[96:97]
	s_lshl_b32 s92, s31, 2
	v_lshl_add_u64 v[96:97], v[96:97], 0, s[92:93]
	global_store_dword v[96:97], v98, off
.LBB0_688:
	s_or_b64 exec, exec, s[28:29]
	v_lshlrev_b32_e32 v96, 16, v140
	s_waitcnt lgkmcnt(0)
	v_and_b32_e32 v97, 0xffff0000, v140
	v_lshlrev_b32_e32 v98, 16, v141
	v_and_b32_e32 v99, 0xffff0000, v141
	v_lshlrev_b32_e32 v100, 16, v142
	v_and_b32_e32 v101, 0xffff0000, v142
	v_pk_add_f32 v[92:93], v[92:93], v[96:97]
	v_pk_add_f32 v[94:95], v[94:95], v[98:99]
	v_pk_add_f32 v[98:99], v[88:89], v[100:101]
	v_cvt_pk_bf16_f32 v88, v92, v93
	v_mul_f32_e32 v93, v93, v93
	v_fmac_f32_e32 v93, v92, v92
	v_mul_f32_e32 v92, v95, v95
	v_fmac_f32_e32 v92, v94, v94
	v_lshlrev_b32_e32 v102, 16, v143
	v_and_b32_e32 v103, 0xffff0000, v143
	v_add_f32_e32 v92, v93, v92
	v_mul_f32_e32 v93, v99, v99
	v_pk_add_f32 v[96:97], v[90:91], v[102:103]
	v_fmac_f32_e32 v93, v98, v98
	v_add_f32_e32 v92, v93, v92
	v_mul_f32_e32 v93, v97, v97
	v_fmac_f32_e32 v93, v96, v96
	v_cvt_pk_bf16_f32 v89, v94, v95
	v_add_f32_e32 v100, v93, v92
	v_lshlrev_b32_e32 v92, 16, v136
	v_and_b32_e32 v93, 0xffff0000, v136
	v_lshlrev_b32_e32 v94, 16, v137
	v_and_b32_e32 v95, 0xffff0000, v137
	v_cvt_pk_bf16_f32 v91, v96, v97
	v_lshlrev_b32_e32 v96, 16, v138
	v_and_b32_e32 v97, 0xffff0000, v138
	v_pk_add_f32 v[86:87], v[86:87], v[94:95]
	v_pk_add_f32 v[84:85], v[84:85], v[92:93]
	v_pk_add_f32 v[94:95], v[80:81], v[96:97]
	v_mul_f32_e32 v80, v85, v85
	v_mul_f32_e32 v81, v87, v87
	v_fmac_f32_e32 v80, v84, v84
	v_fmac_f32_e32 v81, v86, v86
	v_cvt_pk_bf16_f32 v90, v98, v99
	v_lshlrev_b32_e32 v98, 16, v139
	v_and_b32_e32 v99, 0xffff0000, v139
	v_add_f32_e32 v80, v80, v81
	v_mul_f32_e32 v81, v95, v95
	v_pk_add_f32 v[92:93], v[82:83], v[98:99]
	v_fmac_f32_e32 v81, v94, v94
	v_add_f32_e32 v80, v81, v80
	v_mul_f32_e32 v81, v93, v93
	v_fmac_f32_e32 v81, v92, v92
	v_add_f32_e32 v80, v81, v80
	v_add_f32_e32 v83, v100, v80
	v_mov_b32_e32 v98, v83
	s_nop 1
	v_permlane16_swap_b32_e32 v98, v83
	v_lshl_add_u64 v[80:81], s[36:37], 0, v[178:179]
	v_lshl_add_u64 v[96:97], v[166:167], 1, v[80:81]
	v_cvt_pk_bf16_f32 v82, v84, v85
	v_cvt_pk_bf16_f32 v84, v94, v95
	s_waitcnt lgkmcnt(0)
	v_add_f32_e32 v80, v83, v98
	v_mov_b32_e32 v81, v80
	s_nop 1
	v_permlane32_swap_b32_e32 v81, v80
	v_cvt_pk_bf16_f32 v83, v86, v87
	v_cvt_pk_bf16_f32 v85, v92, v93
	global_store_dwordx4 v[96:97], v[88:91], off
	global_store_dwordx4 v[96:97], v[82:85], off offset:256
	s_and_saveexec_b64 s[28:29], vcc
	s_cbranch_execz .LBB0_690
	s_waitcnt lgkmcnt(0)
	v_add_f32_e32 v82, v80, v81
	v_lshlrev_b64 v[80:81], 6, v[176:177]
	v_lshl_add_u64 v[80:81], s[12:13], 0, v[80:81]
	v_lshl_add_u64 v[80:81], s[24:25], 2, v[80:81]
	s_lshl_b32 s92, s31, 2
	v_lshl_add_u64 v[80:81], v[80:81], 0, s[92:93]
	global_store_dword v[80:81], v82, off
.LBB0_690:
	s_or_b64 exec, exec, s[28:29]
	v_lshlrev_b32_e32 v80, 16, v132
	s_waitcnt lgkmcnt(0)
	v_and_b32_e32 v81, 0xffff0000, v132
	v_lshlrev_b32_e32 v82, 16, v133
	v_and_b32_e32 v83, 0xffff0000, v133
	v_lshlrev_b32_e32 v84, 16, v134
	v_and_b32_e32 v85, 0xffff0000, v134
	v_pk_add_f32 v[76:77], v[76:77], v[80:81]
	v_pk_add_f32 v[78:79], v[78:79], v[82:83]
	v_pk_add_f32 v[82:83], v[72:73], v[84:85]
	v_cvt_pk_bf16_f32 v72, v76, v77
	v_mul_f32_e32 v77, v77, v77
	v_fmac_f32_e32 v77, v76, v76
	v_mul_f32_e32 v76, v79, v79
	v_fmac_f32_e32 v76, v78, v78
	v_lshlrev_b32_e32 v86, 16, v135
	v_and_b32_e32 v87, 0xffff0000, v135
	v_add_f32_e32 v76, v77, v76
	v_mul_f32_e32 v77, v83, v83
	v_pk_add_f32 v[80:81], v[74:75], v[86:87]
	v_fmac_f32_e32 v77, v82, v82
	v_add_f32_e32 v76, v77, v76
	v_mul_f32_e32 v77, v81, v81
	v_fmac_f32_e32 v77, v80, v80
	v_cvt_pk_bf16_f32 v73, v78, v79
	v_add_f32_e32 v84, v77, v76
	v_lshlrev_b32_e32 v76, 16, v128
	v_and_b32_e32 v77, 0xffff0000, v128
	v_lshlrev_b32_e32 v78, 16, v129
	v_and_b32_e32 v79, 0xffff0000, v129
	v_cvt_pk_bf16_f32 v75, v80, v81
	v_lshlrev_b32_e32 v80, 16, v130
	v_and_b32_e32 v81, 0xffff0000, v130
	v_pk_add_f32 v[70:71], v[70:71], v[78:79]
	v_pk_add_f32 v[68:69], v[68:69], v[76:77]
	v_pk_add_f32 v[78:79], v[64:65], v[80:81]
	v_mul_f32_e32 v64, v69, v69
	v_mul_f32_e32 v65, v71, v71
	v_fmac_f32_e32 v64, v68, v68
	v_fmac_f32_e32 v65, v70, v70
	v_cvt_pk_bf16_f32 v74, v82, v83
	v_lshlrev_b32_e32 v82, 16, v131
	v_and_b32_e32 v83, 0xffff0000, v131
	v_add_f32_e32 v64, v64, v65
	v_mul_f32_e32 v65, v79, v79
	v_pk_add_f32 v[76:77], v[66:67], v[82:83]
	v_fmac_f32_e32 v65, v78, v78
	v_add_f32_e32 v64, v65, v64
	v_mul_f32_e32 v65, v77, v77
	v_fmac_f32_e32 v65, v76, v76
	v_add_f32_e32 v64, v65, v64
	v_add_f32_e32 v67, v84, v64
	v_mov_b32_e32 v82, v67
	s_nop 1
	v_permlane16_swap_b32_e32 v82, v67
	v_lshl_add_u64 v[64:65], s[36:37], 0, v[174:175]
	v_lshl_add_u64 v[80:81], v[166:167], 1, v[64:65]
	v_cvt_pk_bf16_f32 v66, v68, v69
	v_cvt_pk_bf16_f32 v68, v78, v79
	s_waitcnt lgkmcnt(0)
	v_add_f32_e32 v64, v67, v82
	v_mov_b32_e32 v65, v64
	s_nop 1
	v_permlane32_swap_b32_e32 v65, v64
	v_cvt_pk_bf16_f32 v67, v70, v71
	v_cvt_pk_bf16_f32 v69, v76, v77
	global_store_dwordx4 v[80:81], v[72:75], off
	global_store_dwordx4 v[80:81], v[66:69], off offset:256
	s_and_saveexec_b64 s[28:29], vcc
	s_cbranch_execz .LBB0_692
	s_waitcnt lgkmcnt(0)
	v_add_f32_e32 v66, v64, v65
	v_lshlrev_b64 v[64:65], 6, v[172:173]
	v_lshl_add_u64 v[64:65], s[12:13], 0, v[64:65]
	v_lshl_add_u64 v[64:65], s[24:25], 2, v[64:65]
	s_lshl_b32 s92, s31, 2
	v_lshl_add_u64 v[64:65], v[64:65], 0, s[92:93]
	global_store_dword v[64:65], v66, off
.LBB0_692:
	s_or_b64 exec, exec, s[28:29]
	v_add_u32_e32 v104, 0x80, v168
	v_ashrrev_i32_e32 v105, 31, v104
	v_lshlrev_b64 v[110:111], 11, v[104:105]
	s_waitcnt lgkmcnt(0)
	v_lshl_add_u64 v[64:65], v[170:171], 0, v[110:111]
	global_load_dwordx4 v[106:109], v[64:65], off
	global_load_dwordx4 v[88:91], v[64:65], off offset:256
	v_add_u32_e32 v100, 0x90, v168
	v_ashrrev_i32_e32 v101, 31, v100
	v_add_u32_e32 v96, 0xa0, v168
	v_lshlrev_b64 v[102:103], 11, v[100:101]
	v_ashrrev_i32_e32 v97, 31, v96
	v_add_u32_e32 v92, 0xb0, v168
	v_lshl_add_u64 v[64:65], v[170:171], 0, v[102:103]
	v_lshlrev_b64 v[98:99], 11, v[96:97]
	v_ashrrev_i32_e32 v93, 31, v92
	global_load_dwordx4 v[84:87], v[64:65], off
	global_load_dwordx4 v[80:83], v[64:65], off offset:256
	v_lshl_add_u64 v[64:65], v[170:171], 0, v[98:99]
	v_lshlrev_b64 v[94:95], 11, v[92:93]
	global_load_dwordx4 v[76:79], v[64:65], off
	global_load_dwordx4 v[72:75], v[64:65], off offset:256
	v_lshl_add_u64 v[64:65], v[170:171], 0, v[94:95]
	global_load_dwordx4 v[68:71], v[64:65], off
	s_nop 0
	global_load_dwordx4 v[64:67], v[64:65], off offset:256
	v_lshl_add_u64 v[110:111], s[36:37], 0, v[110:111]
	v_lshl_add_u64 v[110:111], v[166:167], 1, v[110:111]
	s_waitcnt vmcnt(7)
	v_lshlrev_b32_e32 v112, 16, v106
	v_and_b32_e32 v113, 0xffff0000, v106
	v_lshlrev_b32_e32 v106, 16, v107
	v_and_b32_e32 v107, 0xffff0000, v107
	v_lshlrev_b32_e32 v114, 16, v108
	v_and_b32_e32 v115, 0xffff0000, v108
	v_lshlrev_b32_e32 v108, 16, v109
	v_and_b32_e32 v109, 0xffff0000, v109
	v_pk_add_f32 v[62:63], v[62:63], v[106:107]
	v_pk_add_f32 v[60:61], v[60:61], v[112:113]
	v_pk_add_f32 v[106:107], v[58:59], v[108:109]
	v_pk_add_f32 v[108:109], v[56:57], v[114:115]
	v_cvt_pk_bf16_f32 v56, v60, v61
	v_cvt_pk_bf16_f32 v57, v62, v63
	v_cvt_pk_bf16_f32 v58, v108, v109
	v_cvt_pk_bf16_f32 v59, v106, v107
	global_store_dwordx4 v[110:111], v[56:59], off
	s_nop 1
	v_mul_f32_e32 v56, v61, v61
	v_mul_f32_e32 v57, v63, v63
	v_fmac_f32_e32 v56, v60, v60
	v_fmac_f32_e32 v57, v62, v62
	v_add_f32_e32 v56, v56, v57
	v_mul_f32_e32 v57, v109, v109
	v_fmac_f32_e32 v57, v108, v108
	v_add_f32_e32 v56, v57, v56
	v_mul_f32_e32 v57, v107, v107
	v_fmac_f32_e32 v57, v106, v106
	v_add_f32_e32 v106, v57, v56
	s_waitcnt vmcnt(7)
	v_lshlrev_b32_e32 v56, 16, v88
	v_and_b32_e32 v57, 0xffff0000, v88
	v_lshlrev_b32_e32 v58, 16, v89
	v_and_b32_e32 v59, 0xffff0000, v89
	v_lshlrev_b32_e32 v60, 16, v90
	v_and_b32_e32 v61, 0xffff0000, v90
	v_lshlrev_b32_e32 v62, 16, v91
	v_and_b32_e32 v63, 0xffff0000, v91
	v_pk_add_f32 v[54:55], v[54:55], v[58:59]
	v_pk_add_f32 v[52:53], v[52:53], v[56:57]
	v_pk_add_f32 v[56:57], v[50:51], v[62:63]
	v_pk_add_f32 v[58:59], v[48:49], v[60:61]
	v_cvt_pk_bf16_f32 v48, v52, v53
	v_cvt_pk_bf16_f32 v49, v54, v55
	v_cvt_pk_bf16_f32 v50, v58, v59
	v_cvt_pk_bf16_f32 v51, v56, v57
	global_store_dwordx4 v[110:111], v[48:51], off offset:256
	s_nop 1
	v_mul_f32_e32 v48, v53, v53
	v_mul_f32_e32 v49, v55, v55
	v_fmac_f32_e32 v48, v52, v52
	v_fmac_f32_e32 v49, v54, v54
	v_add_f32_e32 v48, v48, v49
	v_mul_f32_e32 v49, v59, v59
	v_fmac_f32_e32 v49, v58, v58
	v_add_f32_e32 v48, v49, v48
	v_mul_f32_e32 v49, v57, v57
	v_fmac_f32_e32 v49, v56, v56
	v_add_f32_e32 v48, v49, v48
	v_add_f32_e32 v48, v106, v48
	v_mov_b32_e32 v49, v48
	s_nop 1
	v_permlane16_swap_b32_e32 v49, v48
	s_waitcnt lgkmcnt(0)
	v_add_f32_e32 v48, v48, v49
	v_mov_b32_e32 v49, v48
	s_nop 1
	v_permlane32_swap_b32_e32 v49, v48
	s_and_saveexec_b64 s[28:29], vcc
	s_cbranch_execz .LBB0_694
	s_waitcnt lgkmcnt(0)
	v_add_f32_e32 v50, v48, v49
	v_lshlrev_b64 v[48:49], 6, v[104:105]
	v_lshl_add_u64 v[48:49], s[12:13], 0, v[48:49]
	v_lshl_add_u64 v[48:49], s[24:25], 2, v[48:49]
	s_lshl_b32 s92, s31, 2
	v_lshl_add_u64 v[48:49], v[48:49], 0, s[92:93]
	global_store_dword v[48:49], v50, off
.LBB0_694:
	s_or_b64 exec, exec, s[28:29]
	s_waitcnt vmcnt(7)
	v_lshlrev_b32_e32 v48, 16, v84
	s_waitcnt lgkmcnt(0)
	v_and_b32_e32 v49, 0xffff0000, v84
	v_lshlrev_b32_e32 v50, 16, v85
	v_and_b32_e32 v51, 0xffff0000, v85
	v_lshlrev_b32_e32 v52, 16, v86
	v_and_b32_e32 v53, 0xffff0000, v86
	v_pk_add_f32 v[44:45], v[44:45], v[48:49]
	v_pk_add_f32 v[46:47], v[46:47], v[50:51]
	v_pk_add_f32 v[50:51], v[40:41], v[52:53]
	v_cvt_pk_bf16_f32 v40, v44, v45
	v_mul_f32_e32 v45, v45, v45
	v_fmac_f32_e32 v45, v44, v44
	v_mul_f32_e32 v44, v47, v47
	v_fmac_f32_e32 v44, v46, v46
	v_lshlrev_b32_e32 v54, 16, v87
	v_and_b32_e32 v55, 0xffff0000, v87
	v_add_f32_e32 v44, v45, v44
	v_mul_f32_e32 v45, v51, v51
	v_pk_add_f32 v[48:49], v[42:43], v[54:55]
	v_fmac_f32_e32 v45, v50, v50
	v_add_f32_e32 v44, v45, v44
	v_mul_f32_e32 v45, v49, v49
	v_fmac_f32_e32 v45, v48, v48
	v_cvt_pk_bf16_f32 v41, v46, v47
	v_add_f32_e32 v52, v45, v44
	s_waitcnt vmcnt(6)
	v_lshlrev_b32_e32 v44, 16, v80
	v_and_b32_e32 v45, 0xffff0000, v80
	v_lshlrev_b32_e32 v46, 16, v81
	v_and_b32_e32 v47, 0xffff0000, v81
	v_cvt_pk_bf16_f32 v43, v48, v49
	v_lshlrev_b32_e32 v48, 16, v82
	v_and_b32_e32 v49, 0xffff0000, v82
	v_pk_add_f32 v[38:39], v[38:39], v[46:47]
	v_pk_add_f32 v[36:37], v[36:37], v[44:45]
	v_pk_add_f32 v[46:47], v[32:33], v[48:49]
	v_mul_f32_e32 v32, v37, v37
	v_mul_f32_e32 v33, v39, v39
	v_fmac_f32_e32 v32, v36, v36
	v_fmac_f32_e32 v33, v38, v38
	v_cvt_pk_bf16_f32 v42, v50, v51
	v_lshlrev_b32_e32 v50, 16, v83
	v_and_b32_e32 v51, 0xffff0000, v83
	v_add_f32_e32 v32, v32, v33
	v_mul_f32_e32 v33, v47, v47
	v_pk_add_f32 v[44:45], v[34:35], v[50:51]
	v_fmac_f32_e32 v33, v46, v46
	v_add_f32_e32 v32, v33, v32
	v_mul_f32_e32 v33, v45, v45
	v_fmac_f32_e32 v33, v44, v44
	v_add_f32_e32 v32, v33, v32
	v_add_f32_e32 v35, v52, v32
	v_mov_b32_e32 v50, v35
	s_nop 1
	v_permlane16_swap_b32_e32 v50, v35
	v_lshl_add_u64 v[32:33], s[36:37], 0, v[102:103]
	v_lshl_add_u64 v[48:49], v[166:167], 1, v[32:33]
	v_cvt_pk_bf16_f32 v34, v36, v37
	v_cvt_pk_bf16_f32 v36, v46, v47
	s_waitcnt lgkmcnt(0)
	v_add_f32_e32 v32, v35, v50
	v_mov_b32_e32 v33, v32
	s_nop 1
	v_permlane32_swap_b32_e32 v33, v32
	v_cvt_pk_bf16_f32 v35, v38, v39
	v_cvt_pk_bf16_f32 v37, v44, v45
	global_store_dwordx4 v[48:49], v[40:43], off
	global_store_dwordx4 v[48:49], v[34:37], off offset:256
	s_and_saveexec_b64 s[28:29], vcc
	s_cbranch_execz .LBB0_696
	s_waitcnt lgkmcnt(0)
	v_add_f32_e32 v34, v32, v33
	v_lshlrev_b64 v[32:33], 6, v[100:101]
	v_lshl_add_u64 v[32:33], s[12:13], 0, v[32:33]
	v_lshl_add_u64 v[32:33], s[24:25], 2, v[32:33]
	s_lshl_b32 s92, s31, 2
	v_lshl_add_u64 v[32:33], v[32:33], 0, s[92:93]
	global_store_dword v[32:33], v34, off
.LBB0_696:
	s_or_b64 exec, exec, s[28:29]
	s_waitcnt vmcnt(7)
	v_lshlrev_b32_e32 v32, 16, v76
	s_waitcnt lgkmcnt(0)
	v_and_b32_e32 v33, 0xffff0000, v76
	v_lshlrev_b32_e32 v34, 16, v77
	v_and_b32_e32 v35, 0xffff0000, v77
	v_lshlrev_b32_e32 v36, 16, v78
	v_and_b32_e32 v37, 0xffff0000, v78
	v_pk_add_f32 v[28:29], v[28:29], v[32:33]
	v_pk_add_f32 v[30:31], v[30:31], v[34:35]
	v_pk_add_f32 v[34:35], v[24:25], v[36:37]
	v_cvt_pk_bf16_f32 v24, v28, v29
	v_mul_f32_e32 v29, v29, v29
	v_fmac_f32_e32 v29, v28, v28
	v_mul_f32_e32 v28, v31, v31
	v_fmac_f32_e32 v28, v30, v30
	v_lshlrev_b32_e32 v38, 16, v79
	v_and_b32_e32 v39, 0xffff0000, v79
	v_add_f32_e32 v28, v29, v28
	v_mul_f32_e32 v29, v35, v35
	v_pk_add_f32 v[32:33], v[26:27], v[38:39]
	v_fmac_f32_e32 v29, v34, v34
	v_add_f32_e32 v28, v29, v28
	v_mul_f32_e32 v29, v33, v33
	v_fmac_f32_e32 v29, v32, v32
	v_cvt_pk_bf16_f32 v25, v30, v31
	v_add_f32_e32 v36, v29, v28
	s_waitcnt vmcnt(6)
	v_lshlrev_b32_e32 v28, 16, v72
	v_and_b32_e32 v29, 0xffff0000, v72
	v_lshlrev_b32_e32 v30, 16, v73
	v_and_b32_e32 v31, 0xffff0000, v73
	v_cvt_pk_bf16_f32 v27, v32, v33
	v_lshlrev_b32_e32 v32, 16, v74
	v_and_b32_e32 v33, 0xffff0000, v74
	v_pk_add_f32 v[22:23], v[22:23], v[30:31]
	v_pk_add_f32 v[20:21], v[20:21], v[28:29]
	v_pk_add_f32 v[30:31], v[16:17], v[32:33]
	v_mul_f32_e32 v16, v21, v21
	v_mul_f32_e32 v17, v23, v23
	v_fmac_f32_e32 v16, v20, v20
	v_fmac_f32_e32 v17, v22, v22
	v_cvt_pk_bf16_f32 v26, v34, v35
	v_lshlrev_b32_e32 v34, 16, v75
	v_and_b32_e32 v35, 0xffff0000, v75
	v_add_f32_e32 v16, v16, v17
	v_mul_f32_e32 v17, v31, v31
	v_pk_add_f32 v[28:29], v[18:19], v[34:35]
	v_fmac_f32_e32 v17, v30, v30
	v_add_f32_e32 v16, v17, v16
	v_mul_f32_e32 v17, v29, v29
	v_fmac_f32_e32 v17, v28, v28
	v_add_f32_e32 v16, v17, v16
	v_add_f32_e32 v19, v36, v16
	v_mov_b32_e32 v34, v19
	s_nop 1
	v_permlane16_swap_b32_e32 v34, v19
	v_lshl_add_u64 v[16:17], s[36:37], 0, v[98:99]
	v_lshl_add_u64 v[32:33], v[166:167], 1, v[16:17]
	v_cvt_pk_bf16_f32 v18, v20, v21
	v_cvt_pk_bf16_f32 v20, v30, v31
	s_waitcnt lgkmcnt(0)
	v_add_f32_e32 v16, v19, v34
	v_mov_b32_e32 v17, v16
	s_nop 1
	v_permlane32_swap_b32_e32 v17, v16
	v_cvt_pk_bf16_f32 v19, v22, v23
	v_cvt_pk_bf16_f32 v21, v28, v29
	global_store_dwordx4 v[32:33], v[24:27], off
	global_store_dwordx4 v[32:33], v[18:21], off offset:256
	s_and_saveexec_b64 s[28:29], vcc
	s_cbranch_execz .LBB0_698
	s_waitcnt lgkmcnt(0)
	v_add_f32_e32 v18, v16, v17
	v_lshlrev_b64 v[16:17], 6, v[96:97]
	v_lshl_add_u64 v[16:17], s[12:13], 0, v[16:17]
	v_lshl_add_u64 v[16:17], s[24:25], 2, v[16:17]
	s_lshl_b32 s92, s31, 2
	v_lshl_add_u64 v[16:17], v[16:17], 0, s[92:93]
	global_store_dword v[16:17], v18, off
.LBB0_698:
	s_or_b64 exec, exec, s[28:29]
	s_waitcnt vmcnt(7)
	v_lshlrev_b32_e32 v16, 16, v68
	s_waitcnt lgkmcnt(0)
	v_and_b32_e32 v17, 0xffff0000, v68
	v_lshlrev_b32_e32 v18, 16, v69
	v_and_b32_e32 v19, 0xffff0000, v69
	v_lshlrev_b32_e32 v20, 16, v70
	v_and_b32_e32 v21, 0xffff0000, v70
	v_pk_add_f32 v[12:13], v[12:13], v[16:17]
	v_pk_add_f32 v[14:15], v[14:15], v[18:19]
	v_pk_add_f32 v[18:19], v[8:9], v[20:21]
	v_cvt_pk_bf16_f32 v8, v12, v13
	v_mul_f32_e32 v13, v13, v13
	v_fmac_f32_e32 v13, v12, v12
	v_mul_f32_e32 v12, v15, v15
	v_fmac_f32_e32 v12, v14, v14
	v_lshlrev_b32_e32 v22, 16, v71
	v_and_b32_e32 v23, 0xffff0000, v71
	v_add_f32_e32 v12, v13, v12
	v_mul_f32_e32 v13, v19, v19
	v_pk_add_f32 v[16:17], v[10:11], v[22:23]
	v_fmac_f32_e32 v13, v18, v18
	v_add_f32_e32 v12, v13, v12
	v_mul_f32_e32 v13, v17, v17
	v_fmac_f32_e32 v13, v16, v16
	v_cvt_pk_bf16_f32 v9, v14, v15
	v_add_f32_e32 v20, v13, v12
	s_waitcnt vmcnt(6)
	v_lshlrev_b32_e32 v12, 16, v64
	v_and_b32_e32 v13, 0xffff0000, v64
	v_lshlrev_b32_e32 v14, 16, v65
	v_and_b32_e32 v15, 0xffff0000, v65
	v_cvt_pk_bf16_f32 v11, v16, v17
	v_lshlrev_b32_e32 v16, 16, v66
	v_and_b32_e32 v17, 0xffff0000, v66
	v_pk_add_f32 v[6:7], v[6:7], v[14:15]
	v_pk_add_f32 v[4:5], v[4:5], v[12:13]
	v_pk_add_f32 v[14:15], v[0:1], v[16:17]
	v_mul_f32_e32 v0, v5, v5
	v_mul_f32_e32 v1, v7, v7
	v_fmac_f32_e32 v0, v4, v4
	v_fmac_f32_e32 v1, v6, v6
	v_cvt_pk_bf16_f32 v10, v18, v19
	v_lshlrev_b32_e32 v18, 16, v67
	v_and_b32_e32 v19, 0xffff0000, v67
	v_add_f32_e32 v0, v0, v1
	v_mul_f32_e32 v1, v15, v15
	v_pk_add_f32 v[12:13], v[2:3], v[18:19]
	v_fmac_f32_e32 v1, v14, v14
	v_add_f32_e32 v0, v1, v0
	v_mul_f32_e32 v1, v13, v13
	v_fmac_f32_e32 v1, v12, v12
	v_add_f32_e32 v0, v1, v0
	v_add_f32_e32 v3, v20, v0
	v_mov_b32_e32 v18, v3
	s_nop 1
	v_permlane16_swap_b32_e32 v18, v3
	v_lshl_add_u64 v[0:1], s[36:37], 0, v[94:95]
	v_lshl_add_u64 v[16:17], v[166:167], 1, v[0:1]
	v_cvt_pk_bf16_f32 v2, v4, v5
	v_cvt_pk_bf16_f32 v4, v14, v15
	s_waitcnt lgkmcnt(0)
	v_add_f32_e32 v0, v3, v18
	v_mov_b32_e32 v1, v0
	s_nop 1
	v_permlane32_swap_b32_e32 v1, v0
	v_cvt_pk_bf16_f32 v3, v6, v7
	v_cvt_pk_bf16_f32 v5, v12, v13
	global_store_dwordx4 v[16:17], v[8:11], off
	global_store_dwordx4 v[16:17], v[2:5], off offset:256
	s_and_saveexec_b64 s[28:29], vcc
	s_cbranch_execz .LBB0_700
	s_waitcnt lgkmcnt(0)
	v_add_f32_e32 v2, v0, v1
	v_lshlrev_b64 v[0:1], 6, v[92:93]
	v_lshl_add_u64 v[0:1], s[12:13], 0, v[0:1]
	v_lshl_add_u64 v[0:1], s[24:25], 2, v[0:1]
	s_lshl_b32 s92, s31, 2
	v_lshl_add_u64 v[0:1], v[0:1], 0, s[92:93]
	global_store_dword v[0:1], v2, off

.LBB0_786:
	v_and_b32_e32 v131, 64, v197
	v_xor_b32_e32 v130, 16, v197
	v_add_u32_e32 v131, 64, v131
	v_cmp_lt_i32_e32 vcc, v130, v131
	v_mov_b32_e32 v128, v149
	v_mov_b32_e32 v165, v147
	s_lshl_b32 s4, s55, 8
	v_cndmask_b32_e32 v130, v197, v130, vcc
	s_add_i32 s4, s4, s33
	v_lshlrev_b32_e32 v174, 2, v130
	v_xor_b32_e32 v130, 32, v197
	v_add_u32_e32 v142, s4, v128
	v_lshlrev_b32_e32 v128, 2, v165
	v_cmp_lt_i32_e32 vcc, v130, v131
	v_ashrrev_i32_e32 v129, 31, v128
	v_ashrrev_i32_e32 v143, 31, v142
	v_cndmask_b32_e32 v130, v197, v130, vcc
	v_lshl_add_u64 v[128:129], v[128:129], 2, s[12:13]
	v_lshlrev_b32_e32 v167, 2, v130
	v_lshlrev_b64 v[130:131], 6, v[142:143]
	v_lshl_add_u64 v[130:131], v[128:129], 0, v[130:131]
	global_load_dwordx4 v[178:181], v[130:131], off offset:1024
	global_load_dwordx4 v[182:185], v[130:131], off offset:2048
	global_load_dwordx4 v[186:189], v[130:131], off offset:3072
	v_add_co_u32_e32 v230, vcc, 0x2000, v130
	s_nop 1
	v_addc_co_u32_e32 v231, vcc, 0, v131, vcc
	global_load_dwordx4 v[198:201], v[230:231], off
	global_load_dwordx4 v[218:221], v[230:231], off offset:1024
	global_load_dwordx4 v[222:225], v[230:231], off offset:2048
	global_load_dwordx4 v[226:229], v[230:231], off offset:3072
	global_load_dwordx4 v[150:153], v[130:131], off
	v_add_u32_e32 v144, 16, v142
	v_ashrrev_i32_e32 v145, 31, v144
	s_mov_b32 s4, 0x358637bd
	s_waitcnt vmcnt(0)
	v_mov_b32_e32 v130, v151
	v_mov_b32_e32 v131, v152
	v_mov_b32_e32 v151, v153
	v_pk_add_f32 v[130:131], v[130:131], v[150:151]
	v_lshlrev_b64 v[150:151], 6, v[144:145]
	v_lshl_add_u64 v[150:151], v[128:129], 0, v[150:151]
	v_mov_b32_e32 v150, v178
	v_mov_b32_e32 v151, v179
	v_mov_b32_e32 v152, v180
	v_mov_b32_e32 v153, v181
	v_mov_b32_e32 v156, v151
	v_mov_b32_e32 v157, v152
	v_mov_b32_e32 v151, v153
	v_pk_add_f32 v[150:151], v[156:157], v[150:151]
	v_mov_b32_e32 v153, v130
	v_mov_b32_e32 v152, v150
	v_mov_b32_e32 v130, v151
	v_pk_add_f32 v[130:131], v[152:153], v[130:131]
	v_mov_b32_e32 v151, v131
	s_nop 1
	v_permlane16_swap_b32_e32 v151, v131
	v_mov_b32_e32 v150, v130
	s_nop 1
	v_permlane16_swap_b32_e32 v150, v130
	v_mov_b64_e32 v[156:157], s[4:5]
	v_add_u32_e32 v152, 32, v142
	v_ashrrev_i32_e32 v153, 31, v152
	s_waitcnt lgkmcnt(0)
	v_pk_add_f32 v[130:131], v[130:131], v[150:151]
	v_mov_b32_e32 v151, v131
	s_nop 1
	v_permlane32_swap_b32_e32 v151, v131
	v_mov_b32_e32 v150, v130
	s_nop 1
	v_permlane32_swap_b32_e32 v150, v130
	s_waitcnt lgkmcnt(0)
	v_pk_add_f32 v[130:131], v[130:131], v[150:151]
	s_nop 0
	v_pk_fma_f32 v[130:131], v[130:131], s[66:67], v[156:157] op_sel_hi:[1,0,0]
	v_add_u32_e32 v150, 48, v142
	v_mul_f32_e32 v146, 0x4b800000, v131
	v_cmp_gt_f32_e64 s[4:5], s80, v131
	v_cmp_gt_f32_e32 vcc, s80, v130
	v_ashrrev_i32_e32 v151, 31, v150
	v_cndmask_b32_e64 v131, v131, v146, s[4:5]
	v_rsq_f32_e32 v131, v131
	s_nop 0
	v_mul_f32_e32 v146, 0x45800000, v131
	v_cndmask_b32_e64 v148, v131, v146, s[4:5]
	v_mul_f32_e32 v131, 0x4b800000, v130
	v_cndmask_b32_e32 v130, v130, v131, vcc
	v_rsq_f32_e32 v130, v130
	v_pk_mul_f32 v[124:125], v[124:125], v[148:149] op_sel_hi:[1,0]
	v_pk_mul_f32 v[120:121], v[120:121], v[148:149] op_sel_hi:[1,0]
	v_pk_mul_f32 v[126:127], v[126:127], v[148:149] op_sel_hi:[1,0]
	v_mul_f32_e32 v131, 0x45800000, v130
	v_cndmask_b32_e32 v146, v130, v131, vcc
	v_lshlrev_b64 v[130:131], 6, v[152:153]
	v_lshl_add_u64 v[130:131], v[128:129], 0, v[130:131]
	v_mov_b32_e32 v160, v182
	v_mov_b32_e32 v161, v183
	v_mov_b32_e32 v162, v184
	v_mov_b32_e32 v163, v185
	v_pk_mul_f32 v[118:119], v[118:119], v[148:149] op_sel_hi:[1,0]
	v_pk_mul_f32 v[116:117], v[116:117], v[148:149] op_sel_hi:[1,0]
	v_pk_mul_f32 v[108:109], v[108:109], v[146:147] op_sel_hi:[1,0]
	v_pk_mul_f32 v[110:111], v[110:111], v[146:147] op_sel_hi:[1,0]
	v_pk_mul_f32 v[102:103], v[102:103], v[146:147] op_sel_hi:[1,0]
	v_pk_mul_f32 v[100:101], v[100:101], v[146:147] op_sel_hi:[1,0]
	v_mov_b32_e32 v130, v161
	v_mov_b32_e32 v131, v162
	v_mov_b32_e32 v161, v163
	v_pk_add_f32 v[130:131], v[130:131], v[160:161]
	v_lshlrev_b64 v[160:161], 6, v[150:151]
	v_lshl_add_u64 v[160:161], v[128:129], 0, v[160:161]
	v_mov_b32_e32 v160, v186
	v_mov_b32_e32 v161, v187
	v_mov_b32_e32 v162, v188
	v_mov_b32_e32 v163, v189
	v_mov_b32_e32 v168, v161
	v_mov_b32_e32 v169, v162
	v_mov_b32_e32 v161, v163
	v_pk_add_f32 v[160:161], v[168:169], v[160:161]
	v_mov_b32_e32 v163, v130
	v_mov_b32_e32 v162, v160
	v_mov_b32_e32 v130, v161
	v_pk_add_f32 v[130:131], v[162:163], v[130:131]
	v_mov_b32_e32 v161, v131
	s_nop 1
	v_permlane16_swap_b32_e32 v161, v131
	v_mov_b32_e32 v160, v130
	s_nop 1
	v_permlane16_swap_b32_e32 v160, v130
	v_add_u32_e32 v162, 0x90, v142
	v_ashrrev_i32_e32 v163, 31, v162
	s_waitcnt lgkmcnt(0)
	v_pk_add_f32 v[130:131], v[130:131], v[160:161]
	v_mov_b32_e32 v161, v131
	s_nop 1
	v_permlane32_swap_b32_e32 v161, v131
	v_mov_b32_e32 v160, v130
	s_nop 1
	v_permlane32_swap_b32_e32 v160, v130
	s_waitcnt lgkmcnt(0)
	v_pk_add_f32 v[130:131], v[130:131], v[160:161]
	s_nop 0
	v_pk_fma_f32 v[130:131], v[130:131], s[66:67], v[156:157] op_sel_hi:[1,0,0]
	v_add_u32_e32 v160, 0x80, v142
	v_mul_f32_e32 v154, 0x4b800000, v131
	v_cmp_gt_f32_e64 s[4:5], s80, v131
	v_cmp_gt_f32_e32 vcc, s80, v130
	v_ashrrev_i32_e32 v161, 31, v160
	v_cndmask_b32_e64 v131, v131, v154, s[4:5]
	v_rsq_f32_e32 v131, v131
	s_nop 0
	v_mul_f32_e32 v154, 0x45800000, v131
	v_cndmask_b32_e64 v158, v131, v154, s[4:5]
	v_mul_f32_e32 v131, 0x4b800000, v130
	v_cndmask_b32_e32 v130, v130, v131, vcc
	v_rsq_f32_e32 v130, v130
	v_pk_mul_f32 v[92:93], v[92:93], v[158:159] op_sel_hi:[1,0]
	v_pk_mul_f32 v[94:95], v[94:95], v[158:159] op_sel_hi:[1,0]
	v_pk_mul_f32 v[86:87], v[86:87], v[158:159] op_sel_hi:[1,0]
	v_mul_f32_e32 v131, 0x45800000, v130
	v_cndmask_b32_e32 v154, v130, v131, vcc
	v_lshlrev_b64 v[130:131], 6, v[160:161]
	v_lshl_add_u64 v[130:131], v[128:129], 0, v[130:131]
	v_mov_b32_e32 v168, v198
	v_mov_b32_e32 v169, v199
	v_mov_b32_e32 v170, v200
	v_mov_b32_e32 v171, v201
	v_pk_mul_f32 v[84:85], v[84:85], v[158:159] op_sel_hi:[1,0]
	v_pk_mul_f32 v[76:77], v[76:77], v[154:155] op_sel_hi:[1,0]
	v_pk_mul_f32 v[78:79], v[78:79], v[154:155] op_sel_hi:[1,0]
	v_pk_mul_f32 v[70:71], v[70:71], v[154:155] op_sel_hi:[1,0]
	v_pk_mul_f32 v[68:69], v[68:69], v[154:155] op_sel_hi:[1,0]
	v_mov_b32_e32 v130, v169
	v_mov_b32_e32 v131, v170
	v_mov_b32_e32 v169, v171
	v_pk_add_f32 v[130:131], v[130:131], v[168:169]
	v_lshlrev_b64 v[168:169], 6, v[162:163]
	v_lshl_add_u64 v[168:169], v[128:129], 0, v[168:169]
	v_mov_b32_e32 v168, v218
	v_mov_b32_e32 v169, v219
	v_mov_b32_e32 v170, v220
	v_mov_b32_e32 v171, v221
	v_mov_b32_e32 v172, v169
	v_mov_b32_e32 v173, v170
	v_mov_b32_e32 v169, v171
	v_pk_add_f32 v[168:169], v[172:173], v[168:169]
	v_mov_b32_e32 v171, v130
	v_mov_b32_e32 v170, v168
	v_mov_b32_e32 v130, v169
	v_pk_add_f32 v[130:131], v[170:171], v[130:131]
	v_mov_b32_e32 v169, v131
	s_nop 1
	v_permlane16_swap_b32_e32 v169, v131
	v_mov_b32_e32 v168, v130
	s_nop 1
	v_permlane16_swap_b32_e32 v168, v130
	s_waitcnt lgkmcnt(0)
	v_pk_add_f32 v[130:131], v[130:131], v[168:169]
	v_mov_b32_e32 v169, v131
	s_nop 1
	v_permlane32_swap_b32_e32 v169, v131
	v_mov_b32_e32 v168, v130
	s_nop 1
	v_permlane32_swap_b32_e32 v168, v130
	s_waitcnt lgkmcnt(0)
	v_pk_add_f32 v[130:131], v[130:131], v[168:169]
	s_nop 0
	v_pk_fma_f32 v[130:131], v[130:131], s[66:67], v[156:157] op_sel_hi:[1,0,0]
	v_add_u32_e32 v168, 0xa0, v142
	v_mul_f32_e32 v164, 0x4b800000, v131
	v_cmp_gt_f32_e64 s[4:5], s80, v131
	v_cmp_gt_f32_e32 vcc, s80, v130
	v_ashrrev_i32_e32 v169, 31, v168
	v_cndmask_b32_e64 v131, v131, v164, s[4:5]
	v_rsq_f32_e32 v131, v131
	s_nop 0
	v_mul_f32_e32 v164, 0x45800000, v131
	v_cndmask_b32_e64 v166, v131, v164, s[4:5]
	v_mul_f32_e32 v131, 0x4b800000, v130
	v_cndmask_b32_e32 v130, v130, v131, vcc
	v_rsq_f32_e32 v130, v130
	v_pk_mul_f32 v[60:61], v[60:61], v[166:167] op_sel_hi:[1,0]
	v_pk_mul_f32 v[62:63], v[62:63], v[166:167] op_sel_hi:[1,0]
	v_pk_mul_f32 v[54:55], v[54:55], v[166:167] op_sel_hi:[1,0]
	v_mul_f32_e32 v131, 0x45800000, v130
	v_cndmask_b32_e32 v164, v130, v131, vcc
	v_lshlrev_b64 v[130:131], 6, v[168:169]
	v_lshl_add_u64 v[130:131], v[128:129], 0, v[130:131]
	v_mov_b32_e32 v170, v222
	v_mov_b32_e32 v171, v223
	v_mov_b32_e32 v172, v224
	v_mov_b32_e32 v173, v225
	v_pk_mul_f32 v[52:53], v[52:53], v[166:167] op_sel_hi:[1,0]
	v_pk_mul_f32 v[44:45], v[44:45], v[164:165] op_sel_hi:[1,0]
	v_pk_mul_f32 v[46:47], v[46:47], v[164:165] op_sel_hi:[1,0]
	v_pk_mul_f32 v[38:39], v[38:39], v[164:165] op_sel_hi:[1,0]
	v_pk_mul_f32 v[36:37], v[36:37], v[164:165] op_sel_hi:[1,0]
	v_mov_b32_e32 v130, v171
	v_mov_b32_e32 v131, v172
	v_mov_b32_e32 v171, v173
	v_pk_add_f32 v[172:173], v[130:131], v[170:171]
	v_add_u32_e32 v170, 0xb0, v142
	v_ashrrev_i32_e32 v171, 31, v170
	v_lshlrev_b64 v[130:131], 6, v[170:171]
	v_lshl_add_u64 v[128:129], v[128:129], 0, v[130:131]
	v_mov_b32_e32 v128, v226
	v_mov_b32_e32 v129, v227
	v_mov_b32_e32 v130, v228
	v_mov_b32_e32 v131, v229
	v_mov_b32_e32 v176, v129
	v_mov_b32_e32 v177, v130
	v_mov_b32_e32 v129, v131
	v_pk_add_f32 v[128:129], v[176:177], v[128:129]
	v_mov_b32_e32 v131, v172
	v_mov_b32_e32 v130, v128
	v_mov_b32_e32 v172, v129
	v_pk_add_f32 v[128:129], v[130:131], v[172:173]
	v_mov_b32_e32 v131, v129
	s_nop 1
	v_permlane16_swap_b32_e32 v131, v129
	v_mov_b32_e32 v130, v128
	s_nop 1
	v_permlane16_swap_b32_e32 v130, v128
	v_pk_mul_f32 v[172:173], v[122:123], v[148:149] op_sel_hi:[1,0]
	v_cvt_pk_bf16_f32 v122, v124, v125
	v_cvt_pk_bf16_f32 v124, v120, v121
	v_lshlrev_b64 v[120:121], 9, v[142:143]
	s_waitcnt lgkmcnt(0)
	v_pk_add_f32 v[128:129], v[128:129], v[130:131]
	v_mov_b32_e32 v131, v129
	s_nop 1
	v_permlane32_swap_b32_e32 v131, v129
	v_mov_b32_e32 v130, v128
	s_nop 1
	v_permlane32_swap_b32_e32 v130, v128
	v_cvt_pk_bf16_f32 v123, v126, v127
	v_cvt_pk_bf16_f32 v125, v172, v173
	s_waitcnt lgkmcnt(0)
	v_pk_add_f32 v[128:129], v[128:129], v[130:131]
	s_nop 0
	v_pk_fma_f32 v[128:129], v[128:129], s[66:67], v[156:157] op_sel_hi:[1,0,0]
	s_nop 0
	v_mul_f32_e32 v130, 0x4b800000, v129
	v_cmp_gt_f32_e64 s[4:5], s80, v129
	v_cmp_gt_f32_e32 vcc, s80, v128
	s_nop 0
	v_cndmask_b32_e64 v129, v129, v130, s[4:5]
	v_rsq_f32_e32 v129, v129
	s_nop 0
	v_mul_f32_e32 v130, 0x45800000, v129
	v_cndmask_b32_e64 v130, v129, v130, s[4:5]
	s_lshl_b32 s4, s54, 8
	s_or_b32 s4, s4, s35
	v_lshl_add_u32 v156, v165, 3, s4
	v_readlane_b32 s4, v253, 62
	v_ashrrev_i32_e32 v157, 31, v156
	v_readlane_b32 s5, v253, 63
	v_mul_f32_e32 v129, 0x4b800000, v128
	v_cndmask_b32_e32 v128, v128, v129, vcc
	v_lshl_add_u64 v[126:127], s[4:5], 0, v[120:121]
	v_lshlrev_b64 v[120:121], 1, v[156:157]
	v_lshl_add_u64 v[126:127], v[126:127], 0, v[120:121]
	global_store_dwordx4 v[126:127], v[122:125], off
	v_rsq_f32_e32 v128, v128
	v_pk_mul_f32 v[28:29], v[28:29], v[130:131] op_sel_hi:[1,0]
	v_pk_mul_f32 v[122:123], v[114:115], v[148:149] op_sel_hi:[1,0]
	v_pk_mul_f32 v[114:115], v[112:113], v[148:149] op_sel_hi:[1,0]
	v_cvt_pk_bf16_f32 v112, v116, v117
	v_cvt_pk_bf16_f32 v113, v118, v119
	v_cvt_pk_bf16_f32 v114, v114, v115
	v_cvt_pk_bf16_f32 v115, v122, v123
	global_store_dwordx4 v[126:127], v[112:115], off offset:256
	v_pk_mul_f32 v[30:31], v[30:31], v[130:131] op_sel_hi:[1,0]
	v_mul_f32_e32 v129, 0x45800000, v128
	v_pk_mul_f32 v[112:113], v[106:107], v[146:147] op_sel_hi:[1,0]
	v_pk_mul_f32 v[106:107], v[104:105], v[146:147] op_sel_hi:[1,0]
	v_cvt_pk_bf16_f32 v104, v108, v109
	v_lshlrev_b64 v[108:109], 9, v[144:145]
	v_lshl_add_u64 v[108:109], s[4:5], 0, v[108:109]
	v_cvt_pk_bf16_f32 v105, v110, v111
	v_cvt_pk_bf16_f32 v106, v106, v107
	v_cvt_pk_bf16_f32 v107, v112, v113
	v_lshl_add_u64 v[108:109], v[108:109], 0, v[120:121]
	global_store_dwordx4 v[108:109], v[104:107], off
	v_cndmask_b32_e32 v128, v128, v129, vcc
	v_pk_mul_f32 v[22:23], v[22:23], v[130:131] op_sel_hi:[1,0]
	v_pk_mul_f32 v[104:105], v[98:99], v[146:147] op_sel_hi:[1,0]
	v_pk_mul_f32 v[98:99], v[96:97], v[146:147] op_sel_hi:[1,0]
	v_cvt_pk_bf16_f32 v96, v100, v101
	v_cvt_pk_bf16_f32 v97, v102, v103
	v_cvt_pk_bf16_f32 v98, v98, v99
	v_cvt_pk_bf16_f32 v99, v104, v105
	global_store_dwordx4 v[108:109], v[96:99], off offset:256
	v_pk_mul_f32 v[20:21], v[20:21], v[130:131] op_sel_hi:[1,0]
	v_pk_mul_f32 v[12:13], v[12:13], v[128:129] op_sel_hi:[1,0]
	v_pk_mul_f32 v[96:97], v[90:91], v[158:159] op_sel_hi:[1,0]
	v_pk_mul_f32 v[90:91], v[88:89], v[158:159] op_sel_hi:[1,0]
	v_cvt_pk_bf16_f32 v88, v92, v93
	v_lshlrev_b64 v[92:93], 9, v[152:153]
	v_lshl_add_u64 v[92:93], s[4:5], 0, v[92:93]
	v_cvt_pk_bf16_f32 v89, v94, v95
	v_cvt_pk_bf16_f32 v90, v90, v91
	v_cvt_pk_bf16_f32 v91, v96, v97
	v_lshl_add_u64 v[92:93], v[92:93], 0, v[120:121]
	global_store_dwordx4 v[92:93], v[88:91], off
	v_pk_mul_f32 v[14:15], v[14:15], v[128:129] op_sel_hi:[1,0]
	v_pk_mul_f32 v[6:7], v[6:7], v[128:129] op_sel_hi:[1,0]
	v_pk_mul_f32 v[88:89], v[82:83], v[158:159] op_sel_hi:[1,0]
	v_pk_mul_f32 v[82:83], v[80:81], v[158:159] op_sel_hi:[1,0]
	v_cvt_pk_bf16_f32 v80, v84, v85
	v_cvt_pk_bf16_f32 v81, v86, v87
	v_cvt_pk_bf16_f32 v82, v82, v83
	v_cvt_pk_bf16_f32 v83, v88, v89
	global_store_dwordx4 v[92:93], v[80:83], off offset:256
	v_pk_mul_f32 v[4:5], v[4:5], v[128:129] op_sel_hi:[1,0]
	s_and_b64 vcc, exec, s[0:1]
	v_pk_mul_f32 v[80:81], v[74:75], v[154:155] op_sel_hi:[1,0]
	v_pk_mul_f32 v[74:75], v[72:73], v[154:155] op_sel_hi:[1,0]
	v_cvt_pk_bf16_f32 v72, v76, v77
	v_lshlrev_b64 v[76:77], 9, v[150:151]
	v_lshl_add_u64 v[76:77], s[4:5], 0, v[76:77]
	v_cvt_pk_bf16_f32 v73, v78, v79
	v_cvt_pk_bf16_f32 v74, v74, v75
	v_cvt_pk_bf16_f32 v75, v80, v81
	v_lshl_add_u64 v[76:77], v[76:77], 0, v[120:121]
	global_store_dwordx4 v[76:77], v[72:75], off
	s_nop 1
	v_pk_mul_f32 v[72:73], v[66:67], v[154:155] op_sel_hi:[1,0]
	v_pk_mul_f32 v[66:67], v[64:65], v[154:155] op_sel_hi:[1,0]
	v_cvt_pk_bf16_f32 v64, v68, v69
	v_cvt_pk_bf16_f32 v65, v70, v71
	v_cvt_pk_bf16_f32 v66, v66, v67
	v_cvt_pk_bf16_f32 v67, v72, v73
	global_store_dwordx4 v[76:77], v[64:67], off offset:256
	s_nop 1
	v_pk_mul_f32 v[64:65], v[58:59], v[166:167] op_sel_hi:[1,0]
	v_pk_mul_f32 v[58:59], v[56:57], v[166:167] op_sel_hi:[1,0]
	v_cvt_pk_bf16_f32 v56, v60, v61
	v_lshlrev_b64 v[60:61], 9, v[160:161]
	v_lshl_add_u64 v[60:61], s[4:5], 0, v[60:61]
	v_cvt_pk_bf16_f32 v57, v62, v63
	v_cvt_pk_bf16_f32 v58, v58, v59
	v_cvt_pk_bf16_f32 v59, v64, v65
	v_lshl_add_u64 v[60:61], v[60:61], 0, v[120:121]
	global_store_dwordx4 v[60:61], v[56:59], off
	s_nop 1
	v_pk_mul_f32 v[56:57], v[50:51], v[166:167] op_sel_hi:[1,0]
	v_pk_mul_f32 v[50:51], v[48:49], v[166:167] op_sel_hi:[1,0]
	v_cvt_pk_bf16_f32 v48, v52, v53
	v_cvt_pk_bf16_f32 v49, v54, v55
	v_cvt_pk_bf16_f32 v50, v50, v51
	v_cvt_pk_bf16_f32 v51, v56, v57
	global_store_dwordx4 v[60:61], v[48:51], off offset:256
	s_nop 1
	v_pk_mul_f32 v[48:49], v[42:43], v[164:165] op_sel_hi:[1,0]
	v_pk_mul_f32 v[42:43], v[40:41], v[164:165] op_sel_hi:[1,0]
	v_cvt_pk_bf16_f32 v40, v44, v45
	v_lshlrev_b64 v[44:45], 9, v[162:163]
	v_lshl_add_u64 v[44:45], s[4:5], 0, v[44:45]
	v_cvt_pk_bf16_f32 v41, v46, v47
	v_cvt_pk_bf16_f32 v42, v42, v43
	v_cvt_pk_bf16_f32 v43, v48, v49
	v_lshl_add_u64 v[44:45], v[44:45], 0, v[120:121]
	global_store_dwordx4 v[44:45], v[40:43], off
	s_nop 1
	v_pk_mul_f32 v[40:41], v[34:35], v[164:165] op_sel_hi:[1,0]
	v_pk_mul_f32 v[34:35], v[32:33], v[164:165] op_sel_hi:[1,0]
	v_cvt_pk_bf16_f32 v32, v36, v37
	v_cvt_pk_bf16_f32 v33, v38, v39
	v_cvt_pk_bf16_f32 v34, v34, v35
	v_cvt_pk_bf16_f32 v35, v40, v41
	global_store_dwordx4 v[44:45], v[32:35], off offset:256
	s_nop 1
	v_pk_mul_f32 v[32:33], v[26:27], v[130:131] op_sel_hi:[1,0]
	v_pk_mul_f32 v[26:27], v[24:25], v[130:131] op_sel_hi:[1,0]
	v_cvt_pk_bf16_f32 v24, v28, v29
	v_lshlrev_b64 v[28:29], 9, v[168:169]
	v_lshl_add_u64 v[28:29], s[4:5], 0, v[28:29]
	v_cvt_pk_bf16_f32 v25, v30, v31
	v_cvt_pk_bf16_f32 v26, v26, v27
	v_cvt_pk_bf16_f32 v27, v32, v33
	v_lshl_add_u64 v[28:29], v[28:29], 0, v[120:121]
	global_store_dwordx4 v[28:29], v[24:27], off
	s_nop 1
	v_pk_mul_f32 v[24:25], v[18:19], v[130:131] op_sel_hi:[1,0]
	v_pk_mul_f32 v[18:19], v[16:17], v[130:131] op_sel_hi:[1,0]
	v_cvt_pk_bf16_f32 v16, v20, v21
	v_cvt_pk_bf16_f32 v17, v22, v23
	v_cvt_pk_bf16_f32 v18, v18, v19
	v_cvt_pk_bf16_f32 v19, v24, v25
	global_store_dwordx4 v[28:29], v[16:19], off offset:256
	s_nop 1
	v_pk_mul_f32 v[16:17], v[10:11], v[128:129] op_sel_hi:[1,0]
	v_pk_mul_f32 v[10:11], v[8:9], v[128:129] op_sel_hi:[1,0]
	v_cvt_pk_bf16_f32 v8, v12, v13
	v_lshlrev_b64 v[12:13], 9, v[170:171]
	v_lshl_add_u64 v[12:13], s[4:5], 0, v[12:13]
	v_cvt_pk_bf16_f32 v9, v14, v15
	v_cvt_pk_bf16_f32 v10, v10, v11
	v_cvt_pk_bf16_f32 v11, v16, v17
	v_lshl_add_u64 v[12:13], v[12:13], 0, v[120:121]
	global_store_dwordx4 v[12:13], v[8:11], off
	s_mov_b64 s[4:5], -1
	s_nop 0
	v_pk_mul_f32 v[8:9], v[2:3], v[128:129] op_sel_hi:[1,0]
	v_pk_mul_f32 v[2:3], v[0:1], v[128:129] op_sel_hi:[1,0]
	v_cvt_pk_bf16_f32 v0, v4, v5
	v_cvt_pk_bf16_f32 v1, v6, v7
	v_cvt_pk_bf16_f32 v2, v2, v3
	v_cvt_pk_bf16_f32 v3, v8, v9
	global_store_dwordx4 v[12:13], v[0:3], off offset:256
	s_cbranch_vccnz .LBB0_769
	s_andn2_b64 vcc, exec, s[14:15]
	s_cbranch_vccnz .LBB0_768
	s_barrier
	s_branch .LBB0_768

.LBB0_1059:
	s_lshl_b32 s24, s51, 8
	v_mov_b32_e32 v128, v185
	v_mov_b32_e32 v129, v184
	s_or_b32 s24, s24, s33
	v_and_b32_e32 v130, 64, v197
	v_lshl_add_u32 v166, v129, 3, s24
	s_lshl_b32 s24, s54, 8
	s_add_i32 s24, s24, s31
	v_add_u32_e32 v168, s24, v128
	v_xor_b32_e32 v128, 16, v197
	v_add_u32_e32 v130, 64, v130
	v_cmp_lt_i32_e32 vcc, v128, v130
	v_ashrrev_i32_e32 v167, 31, v166
	v_lshlrev_b64 v[190:191], 1, v[166:167]
	v_cndmask_b32_e32 v128, v197, v128, vcc
	v_lshlrev_b32_e32 v189, 2, v128
	v_xor_b32_e32 v128, 32, v197
	v_cmp_lt_i32_e32 vcc, v128, v130
	v_ashrrev_i32_e32 v169, 31, v168
	v_lshl_add_u64 v[170:171], s[36:37], 0, v[190:191]
	v_cndmask_b32_e32 v128, v197, v128, vcc
	v_lshlrev_b64 v[218:219], 11, v[168:169]
	v_lshlrev_b32_e32 v188, 2, v128
	v_cmp_eq_u32_e32 vcc, 0, v129
	v_lshl_add_u64 v[128:129], v[170:171], 0, v[218:219]
	global_load_dwordx4 v[198:201], v[128:129], off
	global_load_dwordx4 v[152:155], v[128:129], off offset:256
	v_add_u32_e32 v180, 16, v168
	v_ashrrev_i32_e32 v181, 31, v180
	v_add_u32_e32 v176, 32, v168
	v_lshlrev_b64 v[182:183], 11, v[180:181]
	v_ashrrev_i32_e32 v177, 31, v176
	v_add_u32_e32 v172, 48, v168
	v_lshl_add_u64 v[128:129], v[170:171], 0, v[182:183]
	v_lshlrev_b64 v[178:179], 11, v[176:177]
	v_ashrrev_i32_e32 v173, 31, v172
	global_load_dwordx4 v[148:151], v[128:129], off
	global_load_dwordx4 v[144:147], v[128:129], off offset:256
	v_lshl_add_u64 v[128:129], v[170:171], 0, v[178:179]
	v_lshlrev_b64 v[174:175], 11, v[172:173]
	global_load_dwordx4 v[140:143], v[128:129], off
	global_load_dwordx4 v[136:139], v[128:129], off offset:256
	v_lshl_add_u64 v[128:129], v[170:171], 0, v[174:175]
	global_load_dwordx4 v[132:135], v[128:129], off
	s_nop 0
	global_load_dwordx4 v[128:131], v[128:129], off offset:256
	s_lshl_b32 s24, s51, 2
	s_ashr_i32 s25, s24, 31
	s_waitcnt vmcnt(0)
	v_lshlrev_b32_e32 v220, 16, v198
	v_and_b32_e32 v221, 0xffff0000, v198
	v_lshlrev_b32_e32 v198, 16, v199
	v_and_b32_e32 v199, 0xffff0000, v199
	v_lshlrev_b32_e32 v222, 16, v200
	v_and_b32_e32 v223, 0xffff0000, v200
	v_lshlrev_b32_e32 v200, 16, v201
	v_and_b32_e32 v201, 0xffff0000, v201
	v_pk_add_f32 v[198:199], v[122:123], v[198:199]
	v_pk_add_f32 v[220:221], v[120:121], v[220:221]
	v_pk_add_f32 v[126:127], v[126:127], v[200:201]
	v_pk_add_f32 v[124:125], v[124:125], v[222:223]
	v_lshl_add_u64 v[200:201], s[36:37], 0, v[218:219]
	v_cvt_pk_bf16_f32 v120, v220, v221
	v_cvt_pk_bf16_f32 v121, v198, v199
	v_cvt_pk_bf16_f32 v122, v124, v125
	v_cvt_pk_bf16_f32 v123, v126, v127
	v_lshl_add_u64 v[190:191], v[200:201], 0, v[190:191]
	global_store_dwordx4 v[190:191], v[120:123], off
	s_nop 1
	v_mul_f32_e32 v120, v221, v221
	v_mul_f32_e32 v121, v199, v199
	v_fmac_f32_e32 v120, v220, v220
	v_fmac_f32_e32 v121, v198, v198
	v_add_f32_e32 v120, v120, v121
	v_mul_f32_e32 v121, v125, v125
	v_fmac_f32_e32 v121, v124, v124
	v_add_f32_e32 v120, v121, v120
	v_mul_f32_e32 v121, v127, v127
	v_fmac_f32_e32 v121, v126, v126
	v_add_f32_e32 v192, v121, v120
	v_lshlrev_b32_e32 v120, 16, v152
	v_and_b32_e32 v121, 0xffff0000, v152
	v_lshlrev_b32_e32 v122, 16, v153
	v_and_b32_e32 v123, 0xffff0000, v153
	v_lshlrev_b32_e32 v124, 16, v154
	v_and_b32_e32 v125, 0xffff0000, v154
	v_lshlrev_b32_e32 v126, 16, v155
	v_and_b32_e32 v127, 0xffff0000, v155
	v_pk_add_f32 v[118:119], v[118:119], v[122:123]
	v_pk_add_f32 v[116:117], v[116:117], v[120:121]
	v_pk_add_f32 v[120:121], v[114:115], v[126:127]
	v_pk_add_f32 v[122:123], v[112:113], v[124:125]
	v_cvt_pk_bf16_f32 v112, v116, v117
	v_cvt_pk_bf16_f32 v113, v118, v119
	v_cvt_pk_bf16_f32 v114, v122, v123
	v_cvt_pk_bf16_f32 v115, v120, v121
	global_store_dwordx4 v[190:191], v[112:115], off offset:256
	s_nop 1
	v_mul_f32_e32 v112, v117, v117
	v_mul_f32_e32 v113, v119, v119
	v_fmac_f32_e32 v112, v116, v116
	v_fmac_f32_e32 v113, v118, v118
	v_add_f32_e32 v112, v112, v113
	v_mul_f32_e32 v113, v123, v123
	v_fmac_f32_e32 v113, v122, v122
	v_add_f32_e32 v112, v113, v112
	v_mul_f32_e32 v113, v121, v121
	v_fmac_f32_e32 v113, v120, v120
	v_add_f32_e32 v112, v113, v112
	v_add_f32_e32 v112, v192, v112
	v_mov_b32_e32 v113, v112
	s_nop 1
	v_permlane16_swap_b32_e32 v113, v112
	s_waitcnt lgkmcnt(0)
	v_add_f32_e32 v112, v112, v113
	v_mov_b32_e32 v113, v112
	s_nop 1
	v_permlane32_swap_b32_e32 v113, v112
	s_and_saveexec_b64 s[28:29], vcc
	s_cbranch_execz .LBB0_1061
	s_waitcnt lgkmcnt(0)
	v_add_f32_e32 v114, v112, v113
	v_lshlrev_b64 v[112:113], 6, v[168:169]
	v_lshl_add_u64 v[112:113], s[70:71], 0, v[112:113]
	v_lshl_add_u64 v[112:113], s[24:25], 2, v[112:113]
	s_lshl_b32 s92, s26, 2
	v_lshl_add_u64 v[112:113], v[112:113], 0, s[92:93]
	global_store_dword v[112:113], v114, off
.LBB0_1061:
	s_or_b64 exec, exec, s[28:29]
	v_lshlrev_b32_e32 v112, 16, v148
	s_waitcnt lgkmcnt(0)
	v_and_b32_e32 v113, 0xffff0000, v148
	v_lshlrev_b32_e32 v114, 16, v149
	v_and_b32_e32 v115, 0xffff0000, v149
	v_lshlrev_b32_e32 v116, 16, v150
	v_and_b32_e32 v117, 0xffff0000, v150
	v_pk_add_f32 v[108:109], v[108:109], v[112:113]
	v_pk_add_f32 v[110:111], v[110:111], v[114:115]
	v_pk_add_f32 v[114:115], v[104:105], v[116:117]
	v_cvt_pk_bf16_f32 v104, v108, v109
	v_mul_f32_e32 v109, v109, v109
	v_fmac_f32_e32 v109, v108, v108
	v_mul_f32_e32 v108, v111, v111
	v_fmac_f32_e32 v108, v110, v110
	v_lshlrev_b32_e32 v118, 16, v151
	v_and_b32_e32 v119, 0xffff0000, v151
	v_add_f32_e32 v108, v109, v108
	v_mul_f32_e32 v109, v115, v115
	v_pk_add_f32 v[112:113], v[106:107], v[118:119]
	v_fmac_f32_e32 v109, v114, v114
	v_add_f32_e32 v108, v109, v108
	v_mul_f32_e32 v109, v113, v113
	v_fmac_f32_e32 v109, v112, v112
	v_cvt_pk_bf16_f32 v105, v110, v111
	v_add_f32_e32 v116, v109, v108
	v_lshlrev_b32_e32 v108, 16, v144
	v_and_b32_e32 v109, 0xffff0000, v144
	v_lshlrev_b32_e32 v110, 16, v145
	v_and_b32_e32 v111, 0xffff0000, v145
	v_cvt_pk_bf16_f32 v107, v112, v113
	v_lshlrev_b32_e32 v112, 16, v146
	v_and_b32_e32 v113, 0xffff0000, v146
	v_pk_add_f32 v[102:103], v[102:103], v[110:111]
	v_pk_add_f32 v[100:101], v[100:101], v[108:109]
	v_pk_add_f32 v[110:111], v[96:97], v[112:113]
	v_mul_f32_e32 v96, v101, v101
	v_mul_f32_e32 v97, v103, v103
	v_fmac_f32_e32 v96, v100, v100
	v_fmac_f32_e32 v97, v102, v102
	v_cvt_pk_bf16_f32 v106, v114, v115
	v_lshlrev_b32_e32 v114, 16, v147
	v_and_b32_e32 v115, 0xffff0000, v147
	v_add_f32_e32 v96, v96, v97
	v_mul_f32_e32 v97, v111, v111
	v_pk_add_f32 v[108:109], v[98:99], v[114:115]
	v_fmac_f32_e32 v97, v110, v110
	v_add_f32_e32 v96, v97, v96
	v_mul_f32_e32 v97, v109, v109
	v_fmac_f32_e32 v97, v108, v108
	v_add_f32_e32 v96, v97, v96
	v_add_f32_e32 v99, v116, v96
	v_mov_b32_e32 v114, v99
	s_nop 1
	v_permlane16_swap_b32_e32 v114, v99
	v_lshl_add_u64 v[96:97], s[36:37], 0, v[182:183]
	v_lshl_add_u64 v[112:113], v[166:167], 1, v[96:97]
	v_cvt_pk_bf16_f32 v98, v100, v101
	v_cvt_pk_bf16_f32 v100, v110, v111
	s_waitcnt lgkmcnt(0)
	v_add_f32_e32 v96, v99, v114
	v_mov_b32_e32 v97, v96
	s_nop 1
	v_permlane32_swap_b32_e32 v97, v96
	v_cvt_pk_bf16_f32 v99, v102, v103
	v_cvt_pk_bf16_f32 v101, v108, v109
	global_store_dwordx4 v[112:113], v[104:107], off
	global_store_dwordx4 v[112:113], v[98:101], off offset:256
	s_and_saveexec_b64 s[28:29], vcc
	s_cbranch_execz .LBB0_1063
	s_waitcnt lgkmcnt(0)
	v_add_f32_e32 v98, v96, v97
	v_lshlrev_b64 v[96:97], 6, v[180:181]
	v_lshl_add_u64 v[96:97], s[70:71], 0, v[96:97]
	v_lshl_add_u64 v[96:97], s[24:25], 2, v[96:97]
	s_lshl_b32 s92, s26, 2
	v_lshl_add_u64 v[96:97], v[96:97], 0, s[92:93]
	global_store_dword v[96:97], v98, off
.LBB0_1063:
	s_or_b64 exec, exec, s[28:29]
	v_lshlrev_b32_e32 v96, 16, v140
	s_waitcnt lgkmcnt(0)
	v_and_b32_e32 v97, 0xffff0000, v140
	v_lshlrev_b32_e32 v98, 16, v141
	v_and_b32_e32 v99, 0xffff0000, v141
	v_lshlrev_b32_e32 v100, 16, v142
	v_and_b32_e32 v101, 0xffff0000, v142
	v_pk_add_f32 v[92:93], v[92:93], v[96:97]
	v_pk_add_f32 v[94:95], v[94:95], v[98:99]
	v_pk_add_f32 v[98:99], v[88:89], v[100:101]
	v_cvt_pk_bf16_f32 v88, v92, v93
	v_mul_f32_e32 v93, v93, v93
	v_fmac_f32_e32 v93, v92, v92
	v_mul_f32_e32 v92, v95, v95
	v_fmac_f32_e32 v92, v94, v94
	v_lshlrev_b32_e32 v102, 16, v143
	v_and_b32_e32 v103, 0xffff0000, v143
	v_add_f32_e32 v92, v93, v92
	v_mul_f32_e32 v93, v99, v99
	v_pk_add_f32 v[96:97], v[90:91], v[102:103]
	v_fmac_f32_e32 v93, v98, v98
	v_add_f32_e32 v92, v93, v92
	v_mul_f32_e32 v93, v97, v97
	v_fmac_f32_e32 v93, v96, v96
	v_cvt_pk_bf16_f32 v89, v94, v95
	v_add_f32_e32 v100, v93, v92
	v_lshlrev_b32_e32 v92, 16, v136
	v_and_b32_e32 v93, 0xffff0000, v136
	v_lshlrev_b32_e32 v94, 16, v137
	v_and_b32_e32 v95, 0xffff0000, v137
	v_cvt_pk_bf16_f32 v91, v96, v97
	v_lshlrev_b32_e32 v96, 16, v138
	v_and_b32_e32 v97, 0xffff0000, v138
	v_pk_add_f32 v[86:87], v[86:87], v[94:95]
	v_pk_add_f32 v[84:85], v[84:85], v[92:93]
	v_pk_add_f32 v[94:95], v[80:81], v[96:97]
	v_mul_f32_e32 v80, v85, v85
	v_mul_f32_e32 v81, v87, v87
	v_fmac_f32_e32 v80, v84, v84
	v_fmac_f32_e32 v81, v86, v86
	v_cvt_pk_bf16_f32 v90, v98, v99
	v_lshlrev_b32_e32 v98, 16, v139
	v_and_b32_e32 v99, 0xffff0000, v139
	v_add_f32_e32 v80, v80, v81
	v_mul_f32_e32 v81, v95, v95
	v_pk_add_f32 v[92:93], v[82:83], v[98:99]
	v_fmac_f32_e32 v81, v94, v94
	v_add_f32_e32 v80, v81, v80
	v_mul_f32_e32 v81, v93, v93
	v_fmac_f32_e32 v81, v92, v92
	v_add_f32_e32 v80, v81, v80
	v_add_f32_e32 v83, v100, v80
	v_mov_b32_e32 v98, v83
	s_nop 1
	v_permlane16_swap_b32_e32 v98, v83
	v_lshl_add_u64 v[80:81], s[36:37], 0, v[178:179]
	v_lshl_add_u64 v[96:97], v[166:167], 1, v[80:81]
	v_cvt_pk_bf16_f32 v82, v84, v85
	v_cvt_pk_bf16_f32 v84, v94, v95
	s_waitcnt lgkmcnt(0)
	v_add_f32_e32 v80, v83, v98
	v_mov_b32_e32 v81, v80
	s_nop 1
	v_permlane32_swap_b32_e32 v81, v80
	v_cvt_pk_bf16_f32 v83, v86, v87
	v_cvt_pk_bf16_f32 v85, v92, v93
	global_store_dwordx4 v[96:97], v[88:91], off
	global_store_dwordx4 v[96:97], v[82:85], off offset:256
	s_and_saveexec_b64 s[28:29], vcc
	s_cbranch_execz .LBB0_1065
	s_waitcnt lgkmcnt(0)
	v_add_f32_e32 v82, v80, v81
	v_lshlrev_b64 v[80:81], 6, v[176:177]
	v_lshl_add_u64 v[80:81], s[70:71], 0, v[80:81]
	v_lshl_add_u64 v[80:81], s[24:25], 2, v[80:81]
	s_lshl_b32 s92, s26, 2
	v_lshl_add_u64 v[80:81], v[80:81], 0, s[92:93]
	global_store_dword v[80:81], v82, off
.LBB0_1065:
	s_or_b64 exec, exec, s[28:29]
	v_lshlrev_b32_e32 v80, 16, v132
	s_waitcnt lgkmcnt(0)
	v_and_b32_e32 v81, 0xffff0000, v132
	v_lshlrev_b32_e32 v82, 16, v133
	v_and_b32_e32 v83, 0xffff0000, v133
	v_lshlrev_b32_e32 v84, 16, v134
	v_and_b32_e32 v85, 0xffff0000, v134
	v_pk_add_f32 v[76:77], v[76:77], v[80:81]
	v_pk_add_f32 v[78:79], v[78:79], v[82:83]
	v_pk_add_f32 v[82:83], v[72:73], v[84:85]
	v_cvt_pk_bf16_f32 v72, v76, v77
	v_mul_f32_e32 v77, v77, v77
	v_fmac_f32_e32 v77, v76, v76
	v_mul_f32_e32 v76, v79, v79
	v_fmac_f32_e32 v76, v78, v78
	v_lshlrev_b32_e32 v86, 16, v135
	v_and_b32_e32 v87, 0xffff0000, v135
	v_add_f32_e32 v76, v77, v76
	v_mul_f32_e32 v77, v83, v83
	v_pk_add_f32 v[80:81], v[74:75], v[86:87]
	v_fmac_f32_e32 v77, v82, v82
	v_add_f32_e32 v76, v77, v76
	v_mul_f32_e32 v77, v81, v81
	v_fmac_f32_e32 v77, v80, v80
	v_cvt_pk_bf16_f32 v73, v78, v79
	v_add_f32_e32 v84, v77, v76
	v_lshlrev_b32_e32 v76, 16, v128
	v_and_b32_e32 v77, 0xffff0000, v128
	v_lshlrev_b32_e32 v78, 16, v129
	v_and_b32_e32 v79, 0xffff0000, v129
	v_cvt_pk_bf16_f32 v75, v80, v81
	v_lshlrev_b32_e32 v80, 16, v130
	v_and_b32_e32 v81, 0xffff0000, v130
	v_pk_add_f32 v[70:71], v[70:71], v[78:79]
	v_pk_add_f32 v[68:69], v[68:69], v[76:77]
	v_pk_add_f32 v[78:79], v[64:65], v[80:81]
	v_mul_f32_e32 v64, v69, v69
	v_mul_f32_e32 v65, v71, v71
	v_fmac_f32_e32 v64, v68, v68
	v_fmac_f32_e32 v65, v70, v70
	v_cvt_pk_bf16_f32 v74, v82, v83
	v_lshlrev_b32_e32 v82, 16, v131
	v_and_b32_e32 v83, 0xffff0000, v131
	v_add_f32_e32 v64, v64, v65
	v_mul_f32_e32 v65, v79, v79
	v_pk_add_f32 v[76:77], v[66:67], v[82:83]
	v_fmac_f32_e32 v65, v78, v78
	v_add_f32_e32 v64, v65, v64
	v_mul_f32_e32 v65, v77, v77
	v_fmac_f32_e32 v65, v76, v76
	v_add_f32_e32 v64, v65, v64
	v_add_f32_e32 v67, v84, v64
	v_mov_b32_e32 v82, v67
	s_nop 1
	v_permlane16_swap_b32_e32 v82, v67
	v_lshl_add_u64 v[64:65], s[36:37], 0, v[174:175]
	v_lshl_add_u64 v[80:81], v[166:167], 1, v[64:65]
	v_cvt_pk_bf16_f32 v66, v68, v69
	v_cvt_pk_bf16_f32 v68, v78, v79
	s_waitcnt lgkmcnt(0)
	v_add_f32_e32 v64, v67, v82
	v_mov_b32_e32 v65, v64
	s_nop 1
	v_permlane32_swap_b32_e32 v65, v64
	v_cvt_pk_bf16_f32 v67, v70, v71
	v_cvt_pk_bf16_f32 v69, v76, v77
	global_store_dwordx4 v[80:81], v[72:75], off
	global_store_dwordx4 v[80:81], v[66:69], off offset:256
	s_and_saveexec_b64 s[28:29], vcc
	s_cbranch_execz .LBB0_1067
	s_waitcnt lgkmcnt(0)
	v_add_f32_e32 v66, v64, v65
	v_lshlrev_b64 v[64:65], 6, v[172:173]
	v_lshl_add_u64 v[64:65], s[70:71], 0, v[64:65]
	v_lshl_add_u64 v[64:65], s[24:25], 2, v[64:65]
	s_lshl_b32 s92, s26, 2
	v_lshl_add_u64 v[64:65], v[64:65], 0, s[92:93]
	global_store_dword v[64:65], v66, off
.LBB0_1067:
	s_or_b64 exec, exec, s[28:29]
	v_add_u32_e32 v104, 0x80, v168
	v_ashrrev_i32_e32 v105, 31, v104
	v_lshlrev_b64 v[110:111], 11, v[104:105]
	s_waitcnt lgkmcnt(0)
	v_lshl_add_u64 v[64:65], v[170:171], 0, v[110:111]
	global_load_dwordx4 v[106:109], v[64:65], off
	global_load_dwordx4 v[88:91], v[64:65], off offset:256
	v_add_u32_e32 v100, 0x90, v168
	v_ashrrev_i32_e32 v101, 31, v100
	v_add_u32_e32 v96, 0xa0, v168
	v_lshlrev_b64 v[102:103], 11, v[100:101]
	v_ashrrev_i32_e32 v97, 31, v96
	v_add_u32_e32 v92, 0xb0, v168
	v_lshl_add_u64 v[64:65], v[170:171], 0, v[102:103]
	v_lshlrev_b64 v[98:99], 11, v[96:97]
	v_ashrrev_i32_e32 v93, 31, v92
	global_load_dwordx4 v[84:87], v[64:65], off
	global_load_dwordx4 v[80:83], v[64:65], off offset:256
	v_lshl_add_u64 v[64:65], v[170:171], 0, v[98:99]
	v_lshlrev_b64 v[94:95], 11, v[92:93]
	global_load_dwordx4 v[76:79], v[64:65], off
	global_load_dwordx4 v[72:75], v[64:65], off offset:256
	v_lshl_add_u64 v[64:65], v[170:171], 0, v[94:95]
	global_load_dwordx4 v[68:71], v[64:65], off
	s_nop 0
	global_load_dwordx4 v[64:67], v[64:65], off offset:256
	v_lshl_add_u64 v[110:111], s[36:37], 0, v[110:111]
	v_lshl_add_u64 v[110:111], v[166:167], 1, v[110:111]
	s_waitcnt vmcnt(7)
	v_lshlrev_b32_e32 v112, 16, v106
	v_and_b32_e32 v113, 0xffff0000, v106
	v_lshlrev_b32_e32 v106, 16, v107
	v_and_b32_e32 v107, 0xffff0000, v107
	v_lshlrev_b32_e32 v114, 16, v108
	v_and_b32_e32 v115, 0xffff0000, v108
	v_lshlrev_b32_e32 v108, 16, v109
	v_and_b32_e32 v109, 0xffff0000, v109
	v_pk_add_f32 v[62:63], v[62:63], v[106:107]
	v_pk_add_f32 v[60:61], v[60:61], v[112:113]
	v_pk_add_f32 v[106:107], v[58:59], v[108:109]
	v_pk_add_f32 v[108:109], v[56:57], v[114:115]
	v_cvt_pk_bf16_f32 v56, v60, v61
	v_cvt_pk_bf16_f32 v57, v62, v63
	v_cvt_pk_bf16_f32 v58, v108, v109
	v_cvt_pk_bf16_f32 v59, v106, v107
	global_store_dwordx4 v[110:111], v[56:59], off
	s_nop 1
	v_mul_f32_e32 v56, v61, v61
	v_mul_f32_e32 v57, v63, v63
	v_fmac_f32_e32 v56, v60, v60
	v_fmac_f32_e32 v57, v62, v62
	v_add_f32_e32 v56, v56, v57
	v_mul_f32_e32 v57, v109, v109
	v_fmac_f32_e32 v57, v108, v108
	v_add_f32_e32 v56, v57, v56
	v_mul_f32_e32 v57, v107, v107
	v_fmac_f32_e32 v57, v106, v106
	v_add_f32_e32 v106, v57, v56
	s_waitcnt vmcnt(7)
	v_lshlrev_b32_e32 v56, 16, v88
	v_and_b32_e32 v57, 0xffff0000, v88
	v_lshlrev_b32_e32 v58, 16, v89
	v_and_b32_e32 v59, 0xffff0000, v89
	v_lshlrev_b32_e32 v60, 16, v90
	v_and_b32_e32 v61, 0xffff0000, v90
	v_lshlrev_b32_e32 v62, 16, v91
	v_and_b32_e32 v63, 0xffff0000, v91
	v_pk_add_f32 v[54:55], v[54:55], v[58:59]
	v_pk_add_f32 v[52:53], v[52:53], v[56:57]
	v_pk_add_f32 v[56:57], v[50:51], v[62:63]
	v_pk_add_f32 v[58:59], v[48:49], v[60:61]
	v_cvt_pk_bf16_f32 v48, v52, v53
	v_cvt_pk_bf16_f32 v49, v54, v55
	v_cvt_pk_bf16_f32 v50, v58, v59
	v_cvt_pk_bf16_f32 v51, v56, v57
	global_store_dwordx4 v[110:111], v[48:51], off offset:256
	s_nop 1
	v_mul_f32_e32 v48, v53, v53
	v_mul_f32_e32 v49, v55, v55
	v_fmac_f32_e32 v48, v52, v52
	v_fmac_f32_e32 v49, v54, v54
	v_add_f32_e32 v48, v48, v49
	v_mul_f32_e32 v49, v59, v59
	v_fmac_f32_e32 v49, v58, v58
	v_add_f32_e32 v48, v49, v48
	v_mul_f32_e32 v49, v57, v57
	v_fmac_f32_e32 v49, v56, v56
	v_add_f32_e32 v48, v49, v48
	v_add_f32_e32 v48, v106, v48
	v_mov_b32_e32 v49, v48
	s_nop 1
	v_permlane16_swap_b32_e32 v49, v48
	s_waitcnt lgkmcnt(0)
	v_add_f32_e32 v48, v48, v49
	v_mov_b32_e32 v49, v48
	s_nop 1
	v_permlane32_swap_b32_e32 v49, v48
	s_and_saveexec_b64 s[28:29], vcc
	s_cbranch_execz .LBB0_1069
	s_waitcnt lgkmcnt(0)
	v_add_f32_e32 v50, v48, v49
	v_lshlrev_b64 v[48:49], 6, v[104:105]
	v_lshl_add_u64 v[48:49], s[70:71], 0, v[48:49]
	v_lshl_add_u64 v[48:49], s[24:25], 2, v[48:49]
	s_lshl_b32 s92, s26, 2
	v_lshl_add_u64 v[48:49], v[48:49], 0, s[92:93]
	global_store_dword v[48:49], v50, off
.LBB0_1069:
	s_or_b64 exec, exec, s[28:29]
	s_waitcnt vmcnt(7)
	v_lshlrev_b32_e32 v48, 16, v84
	s_waitcnt lgkmcnt(0)
	v_and_b32_e32 v49, 0xffff0000, v84
	v_lshlrev_b32_e32 v50, 16, v85
	v_and_b32_e32 v51, 0xffff0000, v85
	v_lshlrev_b32_e32 v52, 16, v86
	v_and_b32_e32 v53, 0xffff0000, v86
	v_pk_add_f32 v[44:45], v[44:45], v[48:49]
	v_pk_add_f32 v[46:47], v[46:47], v[50:51]
	v_pk_add_f32 v[50:51], v[40:41], v[52:53]
	v_cvt_pk_bf16_f32 v40, v44, v45
	v_mul_f32_e32 v45, v45, v45
	v_fmac_f32_e32 v45, v44, v44
	v_mul_f32_e32 v44, v47, v47
	v_fmac_f32_e32 v44, v46, v46
	v_lshlrev_b32_e32 v54, 16, v87
	v_and_b32_e32 v55, 0xffff0000, v87
	v_add_f32_e32 v44, v45, v44
	v_mul_f32_e32 v45, v51, v51
	v_pk_add_f32 v[48:49], v[42:43], v[54:55]
	v_fmac_f32_e32 v45, v50, v50
	v_add_f32_e32 v44, v45, v44
	v_mul_f32_e32 v45, v49, v49
	v_fmac_f32_e32 v45, v48, v48
	v_cvt_pk_bf16_f32 v41, v46, v47
	v_add_f32_e32 v52, v45, v44
	s_waitcnt vmcnt(6)
	v_lshlrev_b32_e32 v44, 16, v80
	v_and_b32_e32 v45, 0xffff0000, v80
	v_lshlrev_b32_e32 v46, 16, v81
	v_and_b32_e32 v47, 0xffff0000, v81
	v_cvt_pk_bf16_f32 v43, v48, v49
	v_lshlrev_b32_e32 v48, 16, v82
	v_and_b32_e32 v49, 0xffff0000, v82
	v_pk_add_f32 v[38:39], v[38:39], v[46:47]
	v_pk_add_f32 v[36:37], v[36:37], v[44:45]
	v_pk_add_f32 v[46:47], v[32:33], v[48:49]
	v_mul_f32_e32 v32, v37, v37
	v_mul_f32_e32 v33, v39, v39
	v_fmac_f32_e32 v32, v36, v36
	v_fmac_f32_e32 v33, v38, v38
	v_cvt_pk_bf16_f32 v42, v50, v51
	v_lshlrev_b32_e32 v50, 16, v83
	v_and_b32_e32 v51, 0xffff0000, v83
	v_add_f32_e32 v32, v32, v33
	v_mul_f32_e32 v33, v47, v47
	v_pk_add_f32 v[44:45], v[34:35], v[50:51]
	v_fmac_f32_e32 v33, v46, v46
	v_add_f32_e32 v32, v33, v32
	v_mul_f32_e32 v33, v45, v45
	v_fmac_f32_e32 v33, v44, v44
	v_add_f32_e32 v32, v33, v32
	v_add_f32_e32 v35, v52, v32
	v_mov_b32_e32 v50, v35
	s_nop 1
	v_permlane16_swap_b32_e32 v50, v35
	v_lshl_add_u64 v[32:33], s[36:37], 0, v[102:103]
	v_lshl_add_u64 v[48:49], v[166:167], 1, v[32:33]
	v_cvt_pk_bf16_f32 v34, v36, v37
	v_cvt_pk_bf16_f32 v36, v46, v47
	s_waitcnt lgkmcnt(0)
	v_add_f32_e32 v32, v35, v50
	v_mov_b32_e32 v33, v32
	s_nop 1
	v_permlane32_swap_b32_e32 v33, v32
	v_cvt_pk_bf16_f32 v35, v38, v39
	v_cvt_pk_bf16_f32 v37, v44, v45
	global_store_dwordx4 v[48:49], v[40:43], off
	global_store_dwordx4 v[48:49], v[34:37], off offset:256
	s_and_saveexec_b64 s[28:29], vcc
	s_cbranch_execz .LBB0_1071
	s_waitcnt lgkmcnt(0)
	v_add_f32_e32 v34, v32, v33
	v_lshlrev_b64 v[32:33], 6, v[100:101]
	v_lshl_add_u64 v[32:33], s[70:71], 0, v[32:33]
	v_lshl_add_u64 v[32:33], s[24:25], 2, v[32:33]
	s_lshl_b32 s92, s26, 2
	v_lshl_add_u64 v[32:33], v[32:33], 0, s[92:93]
	global_store_dword v[32:33], v34, off
.LBB0_1071:
	s_or_b64 exec, exec, s[28:29]
	s_waitcnt vmcnt(7)
	v_lshlrev_b32_e32 v32, 16, v76
	s_waitcnt lgkmcnt(0)
	v_and_b32_e32 v33, 0xffff0000, v76
	v_lshlrev_b32_e32 v34, 16, v77
	v_and_b32_e32 v35, 0xffff0000, v77
	v_lshlrev_b32_e32 v36, 16, v78
	v_and_b32_e32 v37, 0xffff0000, v78
	v_pk_add_f32 v[28:29], v[28:29], v[32:33]
	v_pk_add_f32 v[30:31], v[30:31], v[34:35]
	v_pk_add_f32 v[34:35], v[24:25], v[36:37]
	v_cvt_pk_bf16_f32 v24, v28, v29
	v_mul_f32_e32 v29, v29, v29
	v_fmac_f32_e32 v29, v28, v28
	v_mul_f32_e32 v28, v31, v31
	v_fmac_f32_e32 v28, v30, v30
	v_lshlrev_b32_e32 v38, 16, v79
	v_and_b32_e32 v39, 0xffff0000, v79
	v_add_f32_e32 v28, v29, v28
	v_mul_f32_e32 v29, v35, v35
	v_pk_add_f32 v[32:33], v[26:27], v[38:39]
	v_fmac_f32_e32 v29, v34, v34
	v_add_f32_e32 v28, v29, v28
	v_mul_f32_e32 v29, v33, v33
	v_fmac_f32_e32 v29, v32, v32
	v_cvt_pk_bf16_f32 v25, v30, v31
	v_add_f32_e32 v36, v29, v28
	s_waitcnt vmcnt(6)
	v_lshlrev_b32_e32 v28, 16, v72
	v_and_b32_e32 v29, 0xffff0000, v72
	v_lshlrev_b32_e32 v30, 16, v73
	v_and_b32_e32 v31, 0xffff0000, v73
	v_cvt_pk_bf16_f32 v27, v32, v33
	v_lshlrev_b32_e32 v32, 16, v74
	v_and_b32_e32 v33, 0xffff0000, v74
	v_pk_add_f32 v[22:23], v[22:23], v[30:31]
	v_pk_add_f32 v[20:21], v[20:21], v[28:29]
	v_pk_add_f32 v[30:31], v[16:17], v[32:33]
	v_mul_f32_e32 v16, v21, v21
	v_mul_f32_e32 v17, v23, v23
	v_fmac_f32_e32 v16, v20, v20
	v_fmac_f32_e32 v17, v22, v22
	v_cvt_pk_bf16_f32 v26, v34, v35
	v_lshlrev_b32_e32 v34, 16, v75
	v_and_b32_e32 v35, 0xffff0000, v75
	v_add_f32_e32 v16, v16, v17
	v_mul_f32_e32 v17, v31, v31
	v_pk_add_f32 v[28:29], v[18:19], v[34:35]
	v_fmac_f32_e32 v17, v30, v30
	v_add_f32_e32 v16, v17, v16
	v_mul_f32_e32 v17, v29, v29
	v_fmac_f32_e32 v17, v28, v28
	v_add_f32_e32 v16, v17, v16
	v_add_f32_e32 v19, v36, v16
	v_mov_b32_e32 v34, v19
	s_nop 1
	v_permlane16_swap_b32_e32 v34, v19
	v_lshl_add_u64 v[16:17], s[36:37], 0, v[98:99]
	v_lshl_add_u64 v[32:33], v[166:167], 1, v[16:17]
	v_cvt_pk_bf16_f32 v18, v20, v21
	v_cvt_pk_bf16_f32 v20, v30, v31
	s_waitcnt lgkmcnt(0)
	v_add_f32_e32 v16, v19, v34
	v_mov_b32_e32 v17, v16
	s_nop 1
	v_permlane32_swap_b32_e32 v17, v16
	v_cvt_pk_bf16_f32 v19, v22, v23
	v_cvt_pk_bf16_f32 v21, v28, v29
	global_store_dwordx4 v[32:33], v[24:27], off
	global_store_dwordx4 v[32:33], v[18:21], off offset:256
	s_and_saveexec_b64 s[28:29], vcc
	s_cbranch_execz .LBB0_1073
	s_waitcnt lgkmcnt(0)
	v_add_f32_e32 v18, v16, v17
	v_lshlrev_b64 v[16:17], 6, v[96:97]
	v_lshl_add_u64 v[16:17], s[70:71], 0, v[16:17]
	v_lshl_add_u64 v[16:17], s[24:25], 2, v[16:17]
	s_lshl_b32 s92, s26, 2
	v_lshl_add_u64 v[16:17], v[16:17], 0, s[92:93]
	global_store_dword v[16:17], v18, off
.LBB0_1073:
	s_or_b64 exec, exec, s[28:29]
	s_waitcnt vmcnt(7)
	v_lshlrev_b32_e32 v16, 16, v68
	s_waitcnt lgkmcnt(0)
	v_and_b32_e32 v17, 0xffff0000, v68
	v_lshlrev_b32_e32 v18, 16, v69
	v_and_b32_e32 v19, 0xffff0000, v69
	v_lshlrev_b32_e32 v20, 16, v70
	v_and_b32_e32 v21, 0xffff0000, v70
	v_pk_add_f32 v[12:13], v[12:13], v[16:17]
	v_pk_add_f32 v[14:15], v[14:15], v[18:19]
	v_pk_add_f32 v[18:19], v[8:9], v[20:21]
	v_cvt_pk_bf16_f32 v8, v12, v13
	v_mul_f32_e32 v13, v13, v13
	v_fmac_f32_e32 v13, v12, v12
	v_mul_f32_e32 v12, v15, v15
	v_fmac_f32_e32 v12, v14, v14
	v_lshlrev_b32_e32 v22, 16, v71
	v_and_b32_e32 v23, 0xffff0000, v71
	v_add_f32_e32 v12, v13, v12
	v_mul_f32_e32 v13, v19, v19
	v_pk_add_f32 v[16:17], v[10:11], v[22:23]
	v_fmac_f32_e32 v13, v18, v18
	v_add_f32_e32 v12, v13, v12
	v_mul_f32_e32 v13, v17, v17
	v_fmac_f32_e32 v13, v16, v16
	v_cvt_pk_bf16_f32 v9, v14, v15
	v_add_f32_e32 v20, v13, v12
	s_waitcnt vmcnt(6)
	v_lshlrev_b32_e32 v12, 16, v64
	v_and_b32_e32 v13, 0xffff0000, v64
	v_lshlrev_b32_e32 v14, 16, v65
	v_and_b32_e32 v15, 0xffff0000, v65
	v_cvt_pk_bf16_f32 v11, v16, v17
	v_lshlrev_b32_e32 v16, 16, v66
	v_and_b32_e32 v17, 0xffff0000, v66
	v_pk_add_f32 v[6:7], v[6:7], v[14:15]
	v_pk_add_f32 v[4:5], v[4:5], v[12:13]
	v_pk_add_f32 v[14:15], v[0:1], v[16:17]
	v_mul_f32_e32 v0, v5, v5
	v_mul_f32_e32 v1, v7, v7
	v_fmac_f32_e32 v0, v4, v4
	v_fmac_f32_e32 v1, v6, v6
	v_cvt_pk_bf16_f32 v10, v18, v19
	v_lshlrev_b32_e32 v18, 16, v67
	v_and_b32_e32 v19, 0xffff0000, v67
	v_add_f32_e32 v0, v0, v1
	v_mul_f32_e32 v1, v15, v15
	v_pk_add_f32 v[12:13], v[2:3], v[18:19]
	v_fmac_f32_e32 v1, v14, v14
	v_add_f32_e32 v0, v1, v0
	v_mul_f32_e32 v1, v13, v13
	v_fmac_f32_e32 v1, v12, v12
	v_add_f32_e32 v0, v1, v0
	v_add_f32_e32 v3, v20, v0
	v_mov_b32_e32 v18, v3
	s_nop 1
	v_permlane16_swap_b32_e32 v18, v3
	v_lshl_add_u64 v[0:1], s[36:37], 0, v[94:95]
	v_lshl_add_u64 v[16:17], v[166:167], 1, v[0:1]
	v_cvt_pk_bf16_f32 v2, v4, v5
	v_cvt_pk_bf16_f32 v4, v14, v15
	s_waitcnt lgkmcnt(0)
	v_add_f32_e32 v0, v3, v18
	v_mov_b32_e32 v1, v0
	s_nop 1
	v_permlane32_swap_b32_e32 v1, v0
	v_cvt_pk_bf16_f32 v3, v6, v7
	v_cvt_pk_bf16_f32 v5, v12, v13
	global_store_dwordx4 v[16:17], v[8:11], off
	global_store_dwordx4 v[16:17], v[2:5], off offset:256
	s_and_saveexec_b64 s[28:29], vcc
	s_cbranch_execz .LBB0_1075
	s_waitcnt lgkmcnt(0)
	v_add_f32_e32 v2, v0, v1
	v_lshlrev_b64 v[0:1], 6, v[92:93]
	v_lshl_add_u64 v[0:1], s[70:71], 0, v[0:1]
	v_lshl_add_u64 v[0:1], s[24:25], 2, v[0:1]
	s_lshl_b32 s92, s26, 2
	v_lshl_add_u64 v[0:1], v[0:1], 0, s[92:93]
	global_store_dword v[0:1], v2, off

.LBB0_1229:
	s_lshl_b32 s0, s16, 8
	v_mov_b32_e32 v128, v228
	v_mov_b32_e32 v130, v205
	s_or_b32 s0, s0, s54
	v_and_b32_e32 v132, 64, v197
	v_lshl_add_u32 v170, v130, 3, s0
	s_lshl_b32 s0, s20, 8
	s_add_i32 s0, s0, s51
	v_xor_b32_e32 v131, 16, v197
	v_add_u32_e32 v132, 64, v132
	v_add_u32_e32 v172, s0, v128
	v_ashrrev_i32_e32 v171, 31, v170
	v_cmp_lt_i32_e32 vcc, v131, v132
	v_lshlrev_b32_e32 v128, 2, v130
	v_lshlrev_b64 v[220:221], 1, v[170:171]
	v_cndmask_b32_e32 v131, v197, v131, vcc
	v_ashrrev_i32_e32 v173, 31, v172
	v_ashrrev_i32_e32 v129, 31, v128
	v_lshlrev_b32_e32 v232, 2, v131
	v_xor_b32_e32 v131, 32, v197
	v_lshl_add_u64 v[176:177], s[36:37], 0, v[220:221]
	v_lshlrev_b64 v[222:223], 11, v[172:173]
	v_cmp_lt_i32_e32 vcc, v131, v132
	v_lshl_add_u64 v[174:175], v[128:129], 2, s[70:71]
	v_lshl_add_u64 v[128:129], v[176:177], 0, v[222:223]
	v_lshlrev_b64 v[190:191], 6, v[172:173]
	v_cndmask_b32_e32 v131, v197, v131, vcc
	global_load_dwordx4 v[156:159], v[128:129], off
	global_load_dwordx4 v[152:155], v[128:129], off offset:256
	v_lshl_add_u64 v[128:129], v[174:175], 0, v[190:191]
	v_lshlrev_b32_e32 v231, 2, v131
	v_cmp_eq_u32_e32 vcc, 0, v130
	global_load_dwordx4 v[128:131], v[128:129], off
	v_add_u32_e32 v180, 48, v172
	v_ashrrev_i32_e32 v181, 31, v180
	v_lshlrev_b64 v[178:179], 11, v[180:181]
	v_lshlrev_b64 v[180:181], 6, v[180:181]
	v_lshl_add_u64 v[198:199], v[174:175], 0, v[180:181]
	s_lshl_b32 s24, s16, 2
	s_ashr_i32 s25, s24, 31
	v_add_u32_e32 v160, 0x30, v172
	v_ashrrev_i32_e32 v161, 31, v160
	v_lshlrev_b64 v[162:163], 11, v[160:161]
	v_lshl_add_u64 v[162:163], v[176:177], 0, v[162:163]
	global_load_dwordx4 v[164:167], v[162:163], off
	global_load_dwordx4 v[246:249], v[162:163], off offset:256
	global_load_dwordx4 v[198:201], v[198:199], off
	v_add_u32_e32 v160, 0x10, v172
	v_ashrrev_i32_e32 v161, 31, v160
	v_lshlrev_b64 v[162:163], 11, v[160:161]
	v_lshl_add_u64 v[162:163], v[176:177], 0, v[162:163]
	global_load_dwordx4 v[144:147], v[162:163], off
	global_load_dwordx4 v[136:139], v[162:163], off offset:256
	v_lshlrev_b64 v[224:225], 6, v[160:161]
	v_lshl_add_u64 v[224:225], v[174:175], 0, v[224:225]
	global_load_dwordx4 v[224:227], v[224:225], off
	v_add_u32_e32 v160, 0x20, v172
	v_ashrrev_i32_e32 v161, 31, v160
	v_lshlrev_b64 v[162:163], 11, v[160:161]
	v_lshl_add_u64 v[162:163], v[176:177], 0, v[162:163]
	global_load_dwordx4 v[148:151], v[162:163], off
	global_load_dwordx4 v[140:143], v[162:163], off offset:256
	v_lshlrev_b64 v[160:161], 6, v[160:161]
	v_lshl_add_u64 v[160:161], v[174:175], 0, v[160:161]
	global_load_dwordx4 v[160:163], v[160:161], off
	s_waitcnt vmcnt(0)
	v_mov_b32_e32 v132, v129
	v_mov_b32_e32 v133, v130
	v_mov_b32_e32 v129, v131
	v_pk_add_f32 v[132:133], v[132:133], v[128:129]
	v_add_u32_e32 v128, 16, v172
	v_ashrrev_i32_e32 v129, 31, v128
	v_lshlrev_b64 v[182:183], 11, v[128:129]
	v_lshlrev_b64 v[186:187], 6, v[128:129]
	v_lshl_add_u64 v[130:131], v[176:177], 0, v[182:183]
	v_lshl_add_u64 v[128:129], v[174:175], 0, v[186:187]
	s_nop 0
	v_mov_b32_e32 v128, v224
	v_mov_b32_e32 v129, v225
	v_mov_b32_e32 v130, v226
	v_mov_b32_e32 v131, v227
	v_mov_b32_e32 v134, v129
	v_mov_b32_e32 v135, v130
	v_mov_b32_e32 v129, v131
	v_pk_add_f32 v[128:129], v[134:135], v[128:129]
	v_mov_b32_e32 v131, v132
	v_mov_b32_e32 v130, v128
	v_mov_b32_e32 v132, v129
	v_pk_add_f32 v[128:129], v[130:131], v[132:133]
	v_mov_b32_e32 v131, v129
	s_nop 1
	v_permlane16_swap_b32_e32 v131, v129
	v_mov_b32_e32 v130, v128
	s_nop 1
	v_permlane16_swap_b32_e32 v130, v128
	s_waitcnt lgkmcnt(0)
	v_pk_add_f32 v[128:129], v[128:129], v[130:131]
	v_mov_b32_e32 v131, v129
	s_nop 1
	v_permlane32_swap_b32_e32 v131, v129
	v_mov_b32_e32 v130, v128
	s_nop 1
	v_permlane32_swap_b32_e32 v130, v128
	s_waitcnt lgkmcnt(0)
	v_pk_add_f32 v[128:129], v[128:129], v[130:131]
	s_nop 0
	v_pk_fma_f32 v[218:219], v[128:129], s[66:67], v[196:197] op_sel_hi:[1,0,0]
	s_nop 0
	v_mul_f32_e32 v128, 0x4b800000, v219
	v_cmp_gt_f32_e64 s[10:11], s80, v219
	v_cmp_gt_f32_e64 s[0:1], s80, v218
	s_nop 0
	v_cndmask_b32_e64 v128, v219, v128, s[10:11]
	v_rsq_f32_e32 v128, v128
	s_nop 0
	v_mul_f32_e32 v129, 0x45800000, v128
	v_cndmask_b32_e64 v128, v128, v129, s[10:11]
	v_mul_f32_e32 v202, v128, v128
	v_add_u32_e32 v128, 32, v172
	v_ashrrev_i32_e32 v129, 31, v128
	v_lshlrev_b64 v[184:185], 11, v[128:129]
	v_lshlrev_b64 v[188:189], 6, v[128:129]
	v_lshl_add_u64 v[130:131], v[176:177], 0, v[184:185]
	v_lshl_add_u64 v[128:129], v[174:175], 0, v[188:189]
	s_nop 0
	v_mov_b32_e32 v128, v160
	v_mov_b32_e32 v129, v161
	v_mov_b32_e32 v130, v162
	v_mov_b32_e32 v131, v163
	v_mov_b32_e32 v132, v129
	v_mov_b32_e32 v133, v130
	v_mov_b32_e32 v129, v131
	v_pk_add_f32 v[224:225], v[132:133], v[128:129]
	v_lshl_add_u64 v[128:129], v[176:177], 0, v[178:179]
	v_mov_b32_e32 v132, v164
	v_mov_b32_e32 v133, v165
	v_mov_b32_e32 v134, v166
	v_mov_b32_e32 v135, v167
	s_nop 0
	v_mov_b32_e32 v128, v246
	v_mov_b32_e32 v129, v247
	v_mov_b32_e32 v130, v248
	v_mov_b32_e32 v131, v249
	s_nop 0
	v_mov_b32_e32 v226, v199
	v_mov_b32_e32 v227, v200
	v_mov_b32_e32 v199, v201
	v_pk_add_f32 v[198:199], v[226:227], v[198:199]
	v_mov_b32_e32 v201, v224
	v_mov_b32_e32 v200, v198
	v_mov_b32_e32 v224, v199
	v_pk_add_f32 v[198:199], v[200:201], v[224:225]
	v_mov_b32_e32 v201, v199
	s_nop 1
	v_permlane16_swap_b32_e32 v201, v199
	v_mov_b32_e32 v200, v198
	s_nop 1
	v_permlane16_swap_b32_e32 v200, v198
	s_waitcnt lgkmcnt(0)
	v_pk_add_f32 v[224:225], v[198:199], v[200:201]
	v_lshlrev_b32_e32 v198, 16, v156
	v_and_b32_e32 v199, 0xffff0000, v156
	v_lshlrev_b32_e32 v156, 16, v157
	v_and_b32_e32 v157, 0xffff0000, v157
	v_lshlrev_b32_e32 v200, 16, v158
	v_and_b32_e32 v201, 0xffff0000, v158
	v_lshlrev_b32_e32 v158, 16, v159
	v_and_b32_e32 v159, 0xffff0000, v159
	v_pk_fma_f32 v[126:127], v[126:127], v[202:203], v[156:157] op_sel_hi:[1,0,1]
	v_pk_fma_f32 v[124:125], v[124:125], v[202:203], v[198:199] op_sel_hi:[1,0,1]
	v_pk_fma_f32 v[156:157], v[122:123], v[202:203], v[158:159] op_sel_hi:[1,0,1]
	v_pk_fma_f32 v[158:159], v[120:121], v[202:203], v[200:201] op_sel_hi:[1,0,1]
	v_lshl_add_u64 v[198:199], s[36:37], 0, v[222:223]
	v_cvt_pk_bf16_f32 v120, v124, v125
	v_cvt_pk_bf16_f32 v121, v126, v127
	v_cvt_pk_bf16_f32 v122, v158, v159
	v_cvt_pk_bf16_f32 v123, v156, v157
	v_lshl_add_u64 v[198:199], v[198:199], 0, v[220:221]
	global_store_dwordx4 v[198:199], v[120:123], off
	ds_bpermute_b32 v227, v231, v225
	ds_bpermute_b32 v226, v231, v224
	v_mul_f32_e32 v120, v125, v125
	v_mul_f32_e32 v121, v127, v127
	v_fmac_f32_e32 v120, v124, v124
	v_fmac_f32_e32 v121, v126, v126
	v_add_f32_e32 v120, v120, v121
	v_mul_f32_e32 v121, v159, v159
	v_fmac_f32_e32 v121, v158, v158
	v_add_f32_e32 v120, v121, v120
	v_mul_f32_e32 v121, v157, v157
	v_fmac_f32_e32 v121, v156, v156
	v_add_f32_e32 v156, v121, v120
	v_lshlrev_b32_e32 v120, 16, v152
	v_and_b32_e32 v121, 0xffff0000, v152
	v_lshlrev_b32_e32 v122, 16, v153
	v_and_b32_e32 v123, 0xffff0000, v153
	v_lshlrev_b32_e32 v124, 16, v154
	v_and_b32_e32 v125, 0xffff0000, v154
	v_lshlrev_b32_e32 v126, 16, v155
	v_and_b32_e32 v127, 0xffff0000, v155
	v_pk_fma_f32 v[118:119], v[118:119], v[202:203], v[122:123] op_sel_hi:[1,0,1]
	v_pk_fma_f32 v[116:117], v[116:117], v[202:203], v[120:121] op_sel_hi:[1,0,1]
	v_pk_fma_f32 v[120:121], v[114:115], v[202:203], v[126:127] op_sel_hi:[1,0,1]
	v_pk_fma_f32 v[122:123], v[112:113], v[202:203], v[124:125] op_sel_hi:[1,0,1]
	v_cvt_pk_bf16_f32 v112, v116, v117
	v_cvt_pk_bf16_f32 v113, v118, v119
	v_cvt_pk_bf16_f32 v114, v122, v123
	v_cvt_pk_bf16_f32 v115, v120, v121
	global_store_dwordx4 v[198:199], v[112:115], off offset:256
	s_nop 1
	v_mul_f32_e32 v112, v117, v117
	v_mul_f32_e32 v113, v119, v119
	v_fmac_f32_e32 v112, v116, v116
	v_fmac_f32_e32 v113, v118, v118
	v_add_f32_e32 v112, v112, v113
	v_mul_f32_e32 v113, v123, v123
	v_fmac_f32_e32 v113, v122, v122
	v_add_f32_e32 v112, v113, v112
	v_mul_f32_e32 v113, v121, v121
	v_fmac_f32_e32 v113, v120, v120
	v_add_f32_e32 v112, v113, v112
	v_add_f32_e32 v112, v156, v112
	v_mov_b32_e32 v113, v112
	s_nop 1
	v_permlane16_swap_b32_e32 v113, v112
	s_waitcnt lgkmcnt(0)
	v_add_f32_e32 v112, v112, v113
	v_mov_b32_e32 v113, v112
	s_nop 1
	v_permlane32_swap_b32_e32 v113, v112
	s_and_saveexec_b64 s[10:11], vcc
	s_cbranch_execz .LBB0_1231
	v_lshl_add_u64 v[114:115], s[12:13], 0, v[190:191]
	v_lshl_add_u64 v[114:115], s[24:25], 2, v[114:115]
	s_lshl_b32 s92, s49, 2
	v_lshl_add_u64 v[114:115], v[114:115], 0, s[92:93]
	s_waitcnt lgkmcnt(0)
	v_add_f32_e32 v112, v112, v113
	global_store_dword v[114:115], v112, off
.LBB0_1231:
	s_or_b64 exec, exec, s[10:11]
	v_mul_f32_e32 v112, 0x4b800000, v218
	v_cndmask_b32_e64 v112, v218, v112, s[0:1]
	v_rsq_f32_e32 v115, v112
	v_lshlrev_b32_e32 v112, 16, v144
	s_waitcnt lgkmcnt(0)
	v_and_b32_e32 v113, 0xffff0000, v144
	v_lshlrev_b32_e32 v114, 16, v145
	v_mul_f32_e32 v116, 0x45800000, v115
	v_cndmask_b32_e64 v115, v115, v116, s[0:1]
	v_mul_f32_e32 v116, v115, v115
	v_and_b32_e32 v115, 0xffff0000, v145
	v_lshlrev_b32_e32 v118, 16, v146
	v_and_b32_e32 v119, 0xffff0000, v146
	v_pk_fma_f32 v[108:109], v[108:109], v[116:117], v[112:113] op_sel_hi:[1,0,1]
	v_pk_fma_f32 v[110:111], v[110:111], v[116:117], v[114:115] op_sel_hi:[1,0,1]
	v_pk_fma_f32 v[114:115], v[104:105], v[116:117], v[118:119] op_sel_hi:[1,0,1]
	v_cvt_pk_bf16_f32 v104, v108, v109
	v_mul_f32_e32 v109, v109, v109
	v_fmac_f32_e32 v109, v108, v108
	v_mul_f32_e32 v108, v111, v111
	v_fmac_f32_e32 v108, v110, v110
	v_lshlrev_b32_e32 v120, 16, v147
	v_and_b32_e32 v121, 0xffff0000, v147
	v_add_f32_e32 v108, v109, v108
	v_mul_f32_e32 v109, v115, v115
	v_pk_fma_f32 v[112:113], v[106:107], v[116:117], v[120:121] op_sel_hi:[1,0,1]
	v_fmac_f32_e32 v109, v114, v114
	v_add_f32_e32 v108, v109, v108
	v_mul_f32_e32 v109, v113, v113
	v_fmac_f32_e32 v109, v112, v112
	v_cvt_pk_bf16_f32 v105, v110, v111
	v_add_f32_e32 v117, v109, v108
	v_lshlrev_b32_e32 v108, 16, v136
	v_and_b32_e32 v109, 0xffff0000, v136
	v_lshlrev_b32_e32 v110, 16, v137
	v_and_b32_e32 v111, 0xffff0000, v137
	v_cvt_pk_bf16_f32 v107, v112, v113
	v_lshlrev_b32_e32 v112, 16, v138
	v_and_b32_e32 v113, 0xffff0000, v138
	v_pk_fma_f32 v[102:103], v[102:103], v[116:117], v[110:111] op_sel_hi:[1,0,1]
	v_pk_fma_f32 v[100:101], v[100:101], v[116:117], v[108:109] op_sel_hi:[1,0,1]
	v_pk_fma_f32 v[110:111], v[96:97], v[116:117], v[112:113] op_sel_hi:[1,0,1]
	v_mul_f32_e32 v96, v101, v101
	v_mul_f32_e32 v97, v103, v103
	v_fmac_f32_e32 v96, v100, v100
	v_fmac_f32_e32 v97, v102, v102
	v_cvt_pk_bf16_f32 v106, v114, v115
	v_lshlrev_b32_e32 v114, 16, v139
	v_and_b32_e32 v115, 0xffff0000, v139
	v_add_f32_e32 v96, v96, v97
	v_mul_f32_e32 v97, v111, v111
	v_pk_fma_f32 v[108:109], v[98:99], v[116:117], v[114:115] op_sel_hi:[1,0,1]
	v_fmac_f32_e32 v97, v110, v110
	v_add_f32_e32 v96, v97, v96
	v_mul_f32_e32 v97, v109, v109
	v_fmac_f32_e32 v97, v108, v108
	v_add_f32_e32 v96, v97, v96
	v_add_f32_e32 v99, v117, v96
	v_mov_b32_e32 v114, v99
	s_nop 1
	v_permlane16_swap_b32_e32 v114, v99
	v_lshl_add_u64 v[96:97], s[36:37], 0, v[182:183]
	v_lshl_add_u64 v[112:113], v[170:171], 1, v[96:97]
	v_cvt_pk_bf16_f32 v98, v100, v101
	v_cvt_pk_bf16_f32 v100, v110, v111
	s_waitcnt lgkmcnt(0)
	v_add_f32_e32 v96, v99, v114
	v_mov_b32_e32 v97, v96
	s_nop 1
	v_permlane32_swap_b32_e32 v97, v96
	v_cvt_pk_bf16_f32 v99, v102, v103
	v_cvt_pk_bf16_f32 v101, v108, v109
	global_store_dwordx4 v[112:113], v[104:107], off
	global_store_dwordx4 v[112:113], v[98:101], off offset:256
	s_and_saveexec_b64 s[0:1], vcc
	s_cbranch_execz .LBB0_1233
	v_lshl_add_u64 v[98:99], s[12:13], 0, v[186:187]
	v_lshl_add_u64 v[98:99], s[24:25], 2, v[98:99]
	s_lshl_b32 s92, s49, 2
	v_lshl_add_u64 v[98:99], v[98:99], 0, s[92:93]
	s_waitcnt lgkmcnt(0)
	v_add_f32_e32 v96, v96, v97
	global_store_dword v[98:99], v96, off
.LBB0_1233:
	s_or_b64 exec, exec, s[0:1]
	s_waitcnt lgkmcnt(0)
	v_pk_add_f32 v[96:97], v[224:225], v[226:227]
	v_lshlrev_b32_e32 v102, 16, v149
	v_pk_fma_f32 v[96:97], v[96:97], s[66:67], v[196:197] op_sel_hi:[1,0,0]
	v_and_b32_e32 v103, 0xffff0000, v149
	v_mul_f32_e32 v98, 0x4b800000, v97
	v_cmp_gt_f32_e64 s[10:11], s80, v97
	v_lshlrev_b32_e32 v104, 16, v150
	v_and_b32_e32 v105, 0xffff0000, v150
	v_cndmask_b32_e64 v97, v97, v98, s[10:11]
	v_rsq_f32_e32 v97, v97
	v_lshlrev_b32_e32 v98, 16, v148
	v_lshlrev_b32_e32 v106, 16, v151
	v_and_b32_e32 v107, 0xffff0000, v151
	v_mul_f32_e32 v99, 0x45800000, v97
	v_cndmask_b32_e64 v97, v97, v99, s[10:11]
	v_mul_f32_e32 v100, v97, v97
	v_and_b32_e32 v99, 0xffff0000, v148
	v_pk_fma_f32 v[92:93], v[92:93], v[100:101], v[98:99] op_sel_hi:[1,0,1]
	v_pk_fma_f32 v[94:95], v[94:95], v[100:101], v[102:103] op_sel_hi:[1,0,1]
	v_pk_fma_f32 v[102:103], v[88:89], v[100:101], v[104:105] op_sel_hi:[1,0,1]
	v_cvt_pk_bf16_f32 v88, v92, v93
	v_mul_f32_e32 v93, v93, v93
	v_fmac_f32_e32 v93, v92, v92
	v_mul_f32_e32 v92, v95, v95
	v_fmac_f32_e32 v92, v94, v94
	v_add_f32_e32 v92, v93, v92
	v_mul_f32_e32 v93, v103, v103
	v_pk_fma_f32 v[98:99], v[90:91], v[100:101], v[106:107] op_sel_hi:[1,0,1]
	v_fmac_f32_e32 v93, v102, v102
	v_add_f32_e32 v92, v93, v92
	v_mul_f32_e32 v93, v99, v99
	v_fmac_f32_e32 v93, v98, v98
	v_cvt_pk_bf16_f32 v89, v94, v95
	v_add_f32_e32 v97, v93, v92
	v_lshlrev_b32_e32 v92, 16, v140
	v_and_b32_e32 v93, 0xffff0000, v140
	v_lshlrev_b32_e32 v94, 16, v141
	v_and_b32_e32 v95, 0xffff0000, v141
	v_cvt_pk_bf16_f32 v91, v98, v99
	v_lshlrev_b32_e32 v98, 16, v142
	v_and_b32_e32 v99, 0xffff0000, v142
	v_pk_fma_f32 v[86:87], v[86:87], v[100:101], v[94:95] op_sel_hi:[1,0,1]
	v_pk_fma_f32 v[84:85], v[84:85], v[100:101], v[92:93] op_sel_hi:[1,0,1]
	v_pk_fma_f32 v[94:95], v[80:81], v[100:101], v[98:99] op_sel_hi:[1,0,1]
	v_mul_f32_e32 v80, v85, v85
	v_mul_f32_e32 v81, v87, v87
	v_fmac_f32_e32 v80, v84, v84
	v_fmac_f32_e32 v81, v86, v86
	v_cvt_pk_bf16_f32 v90, v102, v103
	v_lshlrev_b32_e32 v102, 16, v143
	v_and_b32_e32 v103, 0xffff0000, v143
	v_add_f32_e32 v80, v80, v81
	v_mul_f32_e32 v81, v95, v95
	v_pk_fma_f32 v[92:93], v[82:83], v[100:101], v[102:103] op_sel_hi:[1,0,1]
	v_fmac_f32_e32 v81, v94, v94
	v_add_f32_e32 v80, v81, v80
	v_mul_f32_e32 v81, v93, v93
	v_fmac_f32_e32 v81, v92, v92
	v_add_f32_e32 v80, v81, v80
	v_add_f32_e32 v83, v97, v80
	v_mov_b32_e32 v97, v83
	s_nop 1
	v_permlane16_swap_b32_e32 v97, v83
	v_lshl_add_u64 v[80:81], s[36:37], 0, v[184:185]
	v_lshl_add_u64 v[98:99], v[170:171], 1, v[80:81]
	v_cmp_gt_f32_e64 s[0:1], s80, v96
	v_cvt_pk_bf16_f32 v82, v84, v85
	s_waitcnt lgkmcnt(0)
	v_add_f32_e32 v80, v83, v97
	v_mov_b32_e32 v81, v80
	s_nop 1
	v_permlane32_swap_b32_e32 v81, v80
	v_cvt_pk_bf16_f32 v83, v86, v87
	v_cvt_pk_bf16_f32 v84, v94, v95
	v_cvt_pk_bf16_f32 v85, v92, v93
	global_store_dwordx4 v[98:99], v[88:91], off
	global_store_dwordx4 v[98:99], v[82:85], off offset:256
	s_and_saveexec_b64 s[10:11], vcc
	s_cbranch_execz .LBB0_1235
	v_lshl_add_u64 v[82:83], s[12:13], 0, v[188:189]
	v_lshl_add_u64 v[82:83], s[24:25], 2, v[82:83]
	s_lshl_b32 s92, s49, 2
	v_lshl_add_u64 v[82:83], v[82:83], 0, s[92:93]
	s_waitcnt lgkmcnt(0)
	v_add_f32_e32 v80, v80, v81
	global_store_dword v[82:83], v80, off
.LBB0_1235:
	s_or_b64 exec, exec, s[10:11]
	v_mul_f32_e32 v80, 0x4b800000, v96
	v_cndmask_b32_e64 v80, v96, v80, s[0:1]
	v_rsq_f32_e32 v83, v80
	v_lshlrev_b32_e32 v80, 16, v132
	s_waitcnt lgkmcnt(0)
	v_and_b32_e32 v81, 0xffff0000, v132
	v_lshlrev_b32_e32 v82, 16, v133
	v_mul_f32_e32 v84, 0x45800000, v83
	v_cndmask_b32_e64 v83, v83, v84, s[0:1]
	v_mul_f32_e32 v84, v83, v83
	v_and_b32_e32 v83, 0xffff0000, v133
	v_lshlrev_b32_e32 v86, 16, v134
	v_and_b32_e32 v87, 0xffff0000, v134
	v_pk_fma_f32 v[76:77], v[76:77], v[84:85], v[80:81] op_sel_hi:[1,0,1]
	v_pk_fma_f32 v[78:79], v[78:79], v[84:85], v[82:83] op_sel_hi:[1,0,1]
	v_pk_fma_f32 v[82:83], v[72:73], v[84:85], v[86:87] op_sel_hi:[1,0,1]
	v_cvt_pk_bf16_f32 v72, v76, v77
	v_mul_f32_e32 v77, v77, v77
	v_fmac_f32_e32 v77, v76, v76
	v_mul_f32_e32 v76, v79, v79
	v_fmac_f32_e32 v76, v78, v78
	v_lshlrev_b32_e32 v88, 16, v135
	v_and_b32_e32 v89, 0xffff0000, v135
	v_add_f32_e32 v76, v77, v76
	v_mul_f32_e32 v77, v83, v83
	v_pk_fma_f32 v[80:81], v[74:75], v[84:85], v[88:89] op_sel_hi:[1,0,1]
	v_fmac_f32_e32 v77, v82, v82
	v_add_f32_e32 v76, v77, v76
	v_mul_f32_e32 v77, v81, v81
	v_fmac_f32_e32 v77, v80, v80
	v_cvt_pk_bf16_f32 v73, v78, v79
	v_add_f32_e32 v85, v77, v76
	v_lshlrev_b32_e32 v76, 16, v128
	v_and_b32_e32 v77, 0xffff0000, v128
	v_lshlrev_b32_e32 v78, 16, v129
	v_and_b32_e32 v79, 0xffff0000, v129
	v_cvt_pk_bf16_f32 v75, v80, v81
	v_lshlrev_b32_e32 v80, 16, v130
	v_and_b32_e32 v81, 0xffff0000, v130
	v_pk_fma_f32 v[70:71], v[70:71], v[84:85], v[78:79] op_sel_hi:[1,0,1]
	v_pk_fma_f32 v[68:69], v[68:69], v[84:85], v[76:77] op_sel_hi:[1,0,1]
	v_pk_fma_f32 v[78:79], v[64:65], v[84:85], v[80:81] op_sel_hi:[1,0,1]
	v_mul_f32_e32 v64, v69, v69
	v_mul_f32_e32 v65, v71, v71
	v_fmac_f32_e32 v64, v68, v68
	v_fmac_f32_e32 v65, v70, v70
	v_cvt_pk_bf16_f32 v74, v82, v83
	v_lshlrev_b32_e32 v82, 16, v131
	v_and_b32_e32 v83, 0xffff0000, v131
	v_add_f32_e32 v64, v64, v65
	v_mul_f32_e32 v65, v79, v79
	v_pk_fma_f32 v[76:77], v[66:67], v[84:85], v[82:83] op_sel_hi:[1,0,1]
	v_fmac_f32_e32 v65, v78, v78
	v_add_f32_e32 v64, v65, v64
	v_mul_f32_e32 v65, v77, v77
	v_fmac_f32_e32 v65, v76, v76
	v_add_f32_e32 v64, v65, v64
	v_add_f32_e32 v67, v85, v64
	v_mov_b32_e32 v82, v67
	s_nop 1
	v_permlane16_swap_b32_e32 v82, v67
	v_lshl_add_u64 v[64:65], s[36:37], 0, v[178:179]
	v_lshl_add_u64 v[80:81], v[170:171], 1, v[64:65]
	v_cvt_pk_bf16_f32 v66, v68, v69
	v_cvt_pk_bf16_f32 v68, v78, v79
	s_waitcnt lgkmcnt(0)
	v_add_f32_e32 v64, v67, v82
	v_mov_b32_e32 v65, v64
	s_nop 1
	v_permlane32_swap_b32_e32 v65, v64
	v_cvt_pk_bf16_f32 v67, v70, v71
	v_cvt_pk_bf16_f32 v69, v76, v77
	global_store_dwordx4 v[80:81], v[72:75], off
	global_store_dwordx4 v[80:81], v[66:69], off offset:256
	s_and_saveexec_b64 s[0:1], vcc
	s_cbranch_execz .LBB0_1237
	v_lshl_add_u64 v[66:67], s[12:13], 0, v[180:181]
	v_lshl_add_u64 v[66:67], s[24:25], 2, v[66:67]
	s_lshl_b32 s92, s49, 2
	v_lshl_add_u64 v[66:67], v[66:67], 0, s[92:93]
	s_waitcnt lgkmcnt(0)
	v_add_f32_e32 v64, v64, v65
	global_store_dword v[66:67], v64, off
.LBB0_1237:
	s_or_b64 exec, exec, s[0:1]
	v_add_u32_e32 v64, 0x80, v172
	s_waitcnt lgkmcnt(0)
	v_ashrrev_i32_e32 v65, 31, v64
	v_lshlrev_b64 v[118:119], 11, v[64:65]
	v_lshlrev_b64 v[108:109], 6, v[64:65]
	v_lshl_add_u64 v[66:67], v[176:177], 0, v[118:119]
	v_lshl_add_u64 v[64:65], v[174:175], 0, v[108:109]
	global_load_dwordx4 v[92:95], v[66:67], off
	global_load_dwordx4 v[88:91], v[66:67], off offset:256
	v_add_u32_e32 v98, 0xb0, v172
	global_load_dwordx4 v[64:67], v[64:65], off
	v_ashrrev_i32_e32 v99, 31, v98
	v_lshlrev_b64 v[96:97], 11, v[98:99]
	v_lshlrev_b64 v[98:99], 6, v[98:99]
	v_lshl_add_u64 v[114:115], v[174:175], 0, v[98:99]
	v_add_u32_e32 v132, 0xb0, v172
	v_ashrrev_i32_e32 v133, 31, v132
	v_lshlrev_b64 v[134:135], 11, v[132:133]
	v_lshl_add_u64 v[134:135], v[176:177], 0, v[134:135]
	global_load_dwordx4 v[136:139], v[134:135], off
	global_load_dwordx4 v[140:143], v[134:135], off offset:256
	global_load_dwordx4 v[114:117], v[114:115], off
	v_add_u32_e32 v132, 0x90, v172
	v_ashrrev_i32_e32 v133, 31, v132
	v_lshlrev_b64 v[134:135], 11, v[132:133]
	v_lshl_add_u64 v[134:135], v[176:177], 0, v[134:135]
	global_load_dwordx4 v[80:83], v[134:135], off
	global_load_dwordx4 v[72:75], v[134:135], off offset:256
	v_lshlrev_b64 v[128:129], 6, v[132:133]
	v_lshl_add_u64 v[128:129], v[174:175], 0, v[128:129]
	global_load_dwordx4 v[128:131], v[128:129], off
	v_add_u32_e32 v132, 0xa0, v172
	v_ashrrev_i32_e32 v133, 31, v132
	v_lshlrev_b64 v[134:135], 11, v[132:133]
	v_lshl_add_u64 v[134:135], v[176:177], 0, v[134:135]
	global_load_dwordx4 v[84:87], v[134:135], off
	global_load_dwordx4 v[76:79], v[134:135], off offset:256
	v_lshlrev_b64 v[132:133], 6, v[132:133]
	v_lshl_add_u64 v[132:133], v[174:175], 0, v[132:133]
	global_load_dwordx4 v[132:135], v[132:133], off
	s_waitcnt vmcnt(0)
	v_mov_b32_e32 v68, v65
	v_mov_b32_e32 v69, v66
	v_mov_b32_e32 v65, v67
	v_pk_add_f32 v[68:69], v[68:69], v[64:65]
	v_add_u32_e32 v64, 0x90, v172
	v_ashrrev_i32_e32 v65, 31, v64
	v_lshlrev_b64 v[100:101], 11, v[64:65]
	v_lshlrev_b64 v[104:105], 6, v[64:65]
	v_lshl_add_u64 v[66:67], v[176:177], 0, v[100:101]
	v_lshl_add_u64 v[64:65], v[174:175], 0, v[104:105]
	s_nop 0
	v_mov_b32_e32 v64, v128
	v_mov_b32_e32 v65, v129
	v_mov_b32_e32 v66, v130
	v_mov_b32_e32 v67, v131
	v_mov_b32_e32 v70, v65
	v_mov_b32_e32 v71, v66
	v_mov_b32_e32 v65, v67
	v_pk_add_f32 v[64:65], v[70:71], v[64:65]
	v_mov_b32_e32 v67, v68
	v_mov_b32_e32 v66, v64
	v_mov_b32_e32 v68, v65
	v_pk_add_f32 v[64:65], v[66:67], v[68:69]
	v_mov_b32_e32 v67, v65
	s_nop 1
	v_permlane16_swap_b32_e32 v67, v65
	v_mov_b32_e32 v66, v64
	s_nop 1
	v_permlane16_swap_b32_e32 v66, v64
	s_waitcnt lgkmcnt(0)
	v_pk_add_f32 v[64:65], v[64:65], v[66:67]
	v_mov_b32_e32 v67, v65
	s_nop 1
	v_permlane32_swap_b32_e32 v67, v65
	v_mov_b32_e32 v66, v64
	s_nop 1
	v_permlane32_swap_b32_e32 v66, v64
	s_waitcnt lgkmcnt(0)
	v_pk_add_f32 v[64:65], v[64:65], v[66:67]
	s_nop 0
	v_pk_fma_f32 v[110:111], v[64:65], s[66:67], v[196:197] op_sel_hi:[1,0,0]
	s_nop 0
	v_mul_f32_e32 v64, 0x4b800000, v111
	v_cmp_gt_f32_e64 s[10:11], s80, v111
	v_cmp_gt_f32_e64 s[0:1], s80, v110
	s_nop 0
	v_cndmask_b32_e64 v64, v111, v64, s[10:11]
	v_rsq_f32_e32 v64, v64
	s_nop 0
	v_mul_f32_e32 v65, 0x45800000, v64
	v_cndmask_b32_e64 v64, v64, v65, s[10:11]
	v_mul_f32_e32 v112, v64, v64
	v_add_u32_e32 v64, 0xa0, v172
	v_ashrrev_i32_e32 v65, 31, v64
	v_lshlrev_b64 v[102:103], 11, v[64:65]
	v_lshlrev_b64 v[106:107], 6, v[64:65]
	v_lshl_add_u64 v[66:67], v[176:177], 0, v[102:103]
	v_lshl_add_u64 v[64:65], v[174:175], 0, v[106:107]
	s_nop 0
	v_mov_b32_e32 v64, v132
	v_mov_b32_e32 v65, v133
	v_mov_b32_e32 v66, v134
	v_mov_b32_e32 v67, v135
	v_mov_b32_e32 v68, v65
	v_mov_b32_e32 v69, v66
	v_mov_b32_e32 v65, v67
	v_pk_add_f32 v[120:121], v[68:69], v[64:65]
	v_lshl_add_u64 v[64:65], v[176:177], 0, v[96:97]
	v_mov_b32_e32 v68, v136
	v_mov_b32_e32 v69, v137
	v_mov_b32_e32 v70, v138
	v_mov_b32_e32 v71, v139
	s_nop 0
	v_mov_b32_e32 v64, v140
	v_mov_b32_e32 v65, v141
	v_mov_b32_e32 v66, v142
	v_mov_b32_e32 v67, v143
	s_nop 0
	v_mov_b32_e32 v122, v115
	v_mov_b32_e32 v123, v116
	v_mov_b32_e32 v115, v117
	v_pk_add_f32 v[114:115], v[122:123], v[114:115]
	v_mov_b32_e32 v117, v120
	v_mov_b32_e32 v116, v114
	v_mov_b32_e32 v120, v115
	v_pk_add_f32 v[114:115], v[116:117], v[120:121]
	v_lshlrev_b32_e32 v120, 16, v92
	v_and_b32_e32 v121, 0xffff0000, v92
	v_lshlrev_b32_e32 v92, 16, v93
	v_and_b32_e32 v93, 0xffff0000, v93
	v_lshlrev_b32_e32 v122, 16, v94
	v_and_b32_e32 v123, 0xffff0000, v94
	v_lshlrev_b32_e32 v94, 16, v95
	v_and_b32_e32 v95, 0xffff0000, v95
	v_pk_fma_f32 v[62:63], v[62:63], v[112:113], v[92:93] op_sel_hi:[1,0,1]
	v_pk_fma_f32 v[92:93], v[60:61], v[112:113], v[120:121] op_sel_hi:[1,0,1]
	v_pk_fma_f32 v[94:95], v[58:59], v[112:113], v[94:95] op_sel_hi:[1,0,1]
	v_pk_fma_f32 v[120:121], v[56:57], v[112:113], v[122:123] op_sel_hi:[1,0,1]
	v_lshl_add_u64 v[56:57], s[36:37], 0, v[118:119]
	v_cvt_pk_bf16_f32 v58, v92, v93
	v_cvt_pk_bf16_f32 v59, v62, v63
	v_cvt_pk_bf16_f32 v60, v120, v121
	v_cvt_pk_bf16_f32 v61, v94, v95
	v_lshl_add_u64 v[56:57], v[170:171], 1, v[56:57]
	global_store_dwordx4 v[56:57], v[58:61], off
	v_mov_b32_e32 v117, v115
	s_nop 1
	v_permlane16_swap_b32_e32 v117, v115
	v_mov_b32_e32 v116, v114
	s_nop 1
	v_permlane16_swap_b32_e32 v116, v114
	v_mul_f32_e32 v58, v93, v93
	v_mul_f32_e32 v59, v63, v63
	v_fmac_f32_e32 v58, v92, v92
	v_fmac_f32_e32 v59, v62, v62
	v_add_f32_e32 v58, v58, v59
	v_mul_f32_e32 v59, v121, v121
	v_fmac_f32_e32 v59, v120, v120
	v_add_f32_e32 v58, v59, v58
	v_mul_f32_e32 v59, v95, v95
	v_fmac_f32_e32 v59, v94, v94
	v_add_f32_e32 v92, v59, v58
	v_lshlrev_b32_e32 v58, 16, v88
	v_and_b32_e32 v59, 0xffff0000, v88
	v_lshlrev_b32_e32 v60, 16, v89
	v_and_b32_e32 v61, 0xffff0000, v89
	v_lshlrev_b32_e32 v62, 16, v90
	v_and_b32_e32 v63, 0xffff0000, v90
	v_lshlrev_b32_e32 v88, 16, v91
	v_and_b32_e32 v89, 0xffff0000, v91
	v_pk_fma_f32 v[54:55], v[54:55], v[112:113], v[60:61] op_sel_hi:[1,0,1]
	v_pk_fma_f32 v[52:53], v[52:53], v[112:113], v[58:59] op_sel_hi:[1,0,1]
	v_pk_fma_f32 v[58:59], v[50:51], v[112:113], v[88:89] op_sel_hi:[1,0,1]
	v_pk_fma_f32 v[60:61], v[48:49], v[112:113], v[62:63] op_sel_hi:[1,0,1]
	v_cvt_pk_bf16_f32 v48, v52, v53
	v_cvt_pk_bf16_f32 v49, v54, v55
	v_cvt_pk_bf16_f32 v50, v60, v61
	v_cvt_pk_bf16_f32 v51, v58, v59
	global_store_dwordx4 v[56:57], v[48:51], off offset:256
	s_waitcnt lgkmcnt(0)
	v_pk_add_f32 v[114:115], v[114:115], v[116:117]
	ds_bpermute_b32 v117, v231, v115
	v_mul_f32_e32 v48, v53, v53
	v_mul_f32_e32 v49, v55, v55
	v_fmac_f32_e32 v48, v52, v52
	v_fmac_f32_e32 v49, v54, v54
	v_add_f32_e32 v48, v48, v49
	v_mul_f32_e32 v49, v61, v61
	v_fmac_f32_e32 v49, v60, v60
	v_add_f32_e32 v48, v49, v48
	v_mul_f32_e32 v49, v59, v59
	v_fmac_f32_e32 v49, v58, v58
	v_add_f32_e32 v48, v49, v48
	v_add_f32_e32 v48, v92, v48
	v_mov_b32_e32 v49, v48
	s_nop 1
	v_permlane16_swap_b32_e32 v49, v48
	ds_bpermute_b32 v116, v231, v114
	s_waitcnt lgkmcnt(1)
	v_add_f32_e32 v48, v48, v49
	v_mov_b32_e32 v49, v48
	s_nop 1
	v_permlane32_swap_b32_e32 v49, v48
	s_and_saveexec_b64 s[10:11], vcc
	s_cbranch_execz .LBB0_1239
	v_lshl_add_u64 v[50:51], s[12:13], 0, v[108:109]
	v_lshl_add_u64 v[50:51], s[24:25], 2, v[50:51]
	s_lshl_b32 s92, s49, 2
	v_lshl_add_u64 v[50:51], v[50:51], 0, s[92:93]
	s_waitcnt lgkmcnt(0)
	v_add_f32_e32 v48, v48, v49
	global_store_dword v[50:51], v48, off
.LBB0_1239:
	s_or_b64 exec, exec, s[10:11]
	v_mul_f32_e32 v48, 0x4b800000, v110
	v_cndmask_b32_e64 v48, v110, v48, s[0:1]
	v_rsq_f32_e32 v51, v48
	v_lshlrev_b32_e32 v48, 16, v80
	s_waitcnt lgkmcnt(0)
	v_and_b32_e32 v49, 0xffff0000, v80
	v_lshlrev_b32_e32 v50, 16, v81
	v_mul_f32_e32 v52, 0x45800000, v51
	v_cndmask_b32_e64 v51, v51, v52, s[0:1]
	v_mul_f32_e32 v52, v51, v51
	v_and_b32_e32 v51, 0xffff0000, v81
	v_lshlrev_b32_e32 v54, 16, v82
	v_and_b32_e32 v55, 0xffff0000, v82
	v_pk_fma_f32 v[44:45], v[44:45], v[52:53], v[48:49] op_sel_hi:[1,0,1]
	v_pk_fma_f32 v[46:47], v[46:47], v[52:53], v[50:51] op_sel_hi:[1,0,1]
	v_pk_fma_f32 v[50:51], v[40:41], v[52:53], v[54:55] op_sel_hi:[1,0,1]
	v_cvt_pk_bf16_f32 v40, v44, v45
	v_mul_f32_e32 v45, v45, v45
	v_fmac_f32_e32 v45, v44, v44
	v_mul_f32_e32 v44, v47, v47
	v_fmac_f32_e32 v44, v46, v46
	v_lshlrev_b32_e32 v56, 16, v83
	v_and_b32_e32 v57, 0xffff0000, v83
	v_add_f32_e32 v44, v45, v44
	v_mul_f32_e32 v45, v51, v51
	v_pk_fma_f32 v[48:49], v[42:43], v[52:53], v[56:57] op_sel_hi:[1,0,1]
	v_fmac_f32_e32 v45, v50, v50
	v_add_f32_e32 v44, v45, v44
	v_mul_f32_e32 v45, v49, v49
	v_fmac_f32_e32 v45, v48, v48
	v_cvt_pk_bf16_f32 v41, v46, v47
	v_add_f32_e32 v53, v45, v44
	v_lshlrev_b32_e32 v44, 16, v72
	v_and_b32_e32 v45, 0xffff0000, v72
	v_lshlrev_b32_e32 v46, 16, v73
	v_and_b32_e32 v47, 0xffff0000, v73
	v_cvt_pk_bf16_f32 v43, v48, v49
	v_lshlrev_b32_e32 v48, 16, v74
	v_and_b32_e32 v49, 0xffff0000, v74
	v_pk_fma_f32 v[38:39], v[38:39], v[52:53], v[46:47] op_sel_hi:[1,0,1]
	v_pk_fma_f32 v[36:37], v[36:37], v[52:53], v[44:45] op_sel_hi:[1,0,1]
	v_pk_fma_f32 v[46:47], v[32:33], v[52:53], v[48:49] op_sel_hi:[1,0,1]
	v_mul_f32_e32 v32, v37, v37
	v_mul_f32_e32 v33, v39, v39
	v_fmac_f32_e32 v32, v36, v36
	v_fmac_f32_e32 v33, v38, v38
	v_cvt_pk_bf16_f32 v42, v50, v51
	v_lshlrev_b32_e32 v50, 16, v75
	v_and_b32_e32 v51, 0xffff0000, v75
	v_add_f32_e32 v32, v32, v33
	v_mul_f32_e32 v33, v47, v47
	v_pk_fma_f32 v[44:45], v[34:35], v[52:53], v[50:51] op_sel_hi:[1,0,1]
	v_fmac_f32_e32 v33, v46, v46
	v_add_f32_e32 v32, v33, v32
	v_mul_f32_e32 v33, v45, v45
	v_fmac_f32_e32 v33, v44, v44
	v_add_f32_e32 v32, v33, v32
	v_add_f32_e32 v35, v53, v32
	v_mov_b32_e32 v50, v35
	s_nop 1
	v_permlane16_swap_b32_e32 v50, v35
	v_lshl_add_u64 v[32:33], s[36:37], 0, v[100:101]
	v_lshl_add_u64 v[48:49], v[170:171], 1, v[32:33]
	v_cvt_pk_bf16_f32 v34, v36, v37
	v_cvt_pk_bf16_f32 v36, v46, v47
	s_waitcnt lgkmcnt(0)
	v_add_f32_e32 v32, v35, v50
	v_mov_b32_e32 v33, v32
	s_nop 1
	v_permlane32_swap_b32_e32 v33, v32
	v_cvt_pk_bf16_f32 v35, v38, v39
	v_cvt_pk_bf16_f32 v37, v44, v45
	global_store_dwordx4 v[48:49], v[40:43], off
	global_store_dwordx4 v[48:49], v[34:37], off offset:256
	s_and_saveexec_b64 s[0:1], vcc
	s_cbranch_execz .LBB0_1241
	v_lshl_add_u64 v[34:35], s[12:13], 0, v[104:105]
	v_lshl_add_u64 v[34:35], s[24:25], 2, v[34:35]
	s_lshl_b32 s92, s49, 2
	v_lshl_add_u64 v[34:35], v[34:35], 0, s[92:93]
	s_waitcnt lgkmcnt(0)
	v_add_f32_e32 v32, v32, v33
	global_store_dword v[34:35], v32, off
.LBB0_1241:
	s_or_b64 exec, exec, s[0:1]
	s_waitcnt lgkmcnt(0)
	v_pk_add_f32 v[32:33], v[114:115], v[116:117]
	v_lshlrev_b32_e32 v38, 16, v85
	v_pk_fma_f32 v[32:33], v[32:33], s[66:67], v[196:197] op_sel_hi:[1,0,0]
	v_and_b32_e32 v39, 0xffff0000, v85
	v_mul_f32_e32 v34, 0x4b800000, v33
	v_cmp_gt_f32_e64 s[10:11], s80, v33
	v_lshlrev_b32_e32 v40, 16, v86
	v_and_b32_e32 v41, 0xffff0000, v86
	v_cndmask_b32_e64 v33, v33, v34, s[10:11]
	v_rsq_f32_e32 v33, v33
	v_lshlrev_b32_e32 v34, 16, v84
	v_lshlrev_b32_e32 v42, 16, v87
	v_and_b32_e32 v43, 0xffff0000, v87
	v_mul_f32_e32 v35, 0x45800000, v33
	v_cndmask_b32_e64 v33, v33, v35, s[10:11]
	v_mul_f32_e32 v36, v33, v33
	v_and_b32_e32 v35, 0xffff0000, v84
	v_pk_fma_f32 v[28:29], v[28:29], v[36:37], v[34:35] op_sel_hi:[1,0,1]
	v_pk_fma_f32 v[30:31], v[30:31], v[36:37], v[38:39] op_sel_hi:[1,0,1]
	v_pk_fma_f32 v[38:39], v[24:25], v[36:37], v[40:41] op_sel_hi:[1,0,1]
	v_cvt_pk_bf16_f32 v24, v28, v29
	v_mul_f32_e32 v29, v29, v29
	v_fmac_f32_e32 v29, v28, v28
	v_mul_f32_e32 v28, v31, v31
	v_fmac_f32_e32 v28, v30, v30
	v_add_f32_e32 v28, v29, v28
	v_mul_f32_e32 v29, v39, v39
	v_pk_fma_f32 v[34:35], v[26:27], v[36:37], v[42:43] op_sel_hi:[1,0,1]
	v_fmac_f32_e32 v29, v38, v38
	v_add_f32_e32 v28, v29, v28
	v_mul_f32_e32 v29, v35, v35
	v_fmac_f32_e32 v29, v34, v34
	v_cvt_pk_bf16_f32 v25, v30, v31
	v_add_f32_e32 v33, v29, v28
	v_lshlrev_b32_e32 v28, 16, v76
	v_and_b32_e32 v29, 0xffff0000, v76
	v_lshlrev_b32_e32 v30, 16, v77
	v_and_b32_e32 v31, 0xffff0000, v77
	v_cvt_pk_bf16_f32 v27, v34, v35
	v_lshlrev_b32_e32 v34, 16, v78
	v_and_b32_e32 v35, 0xffff0000, v78
	v_pk_fma_f32 v[22:23], v[22:23], v[36:37], v[30:31] op_sel_hi:[1,0,1]
	v_pk_fma_f32 v[20:21], v[20:21], v[36:37], v[28:29] op_sel_hi:[1,0,1]
	v_pk_fma_f32 v[30:31], v[16:17], v[36:37], v[34:35] op_sel_hi:[1,0,1]
	v_mul_f32_e32 v16, v21, v21
	v_mul_f32_e32 v17, v23, v23
	v_fmac_f32_e32 v16, v20, v20
	v_fmac_f32_e32 v17, v22, v22
	v_cvt_pk_bf16_f32 v26, v38, v39
	v_lshlrev_b32_e32 v38, 16, v79
	v_and_b32_e32 v39, 0xffff0000, v79
	v_add_f32_e32 v16, v16, v17
	v_mul_f32_e32 v17, v31, v31
	v_pk_fma_f32 v[28:29], v[18:19], v[36:37], v[38:39] op_sel_hi:[1,0,1]
	v_fmac_f32_e32 v17, v30, v30
	v_add_f32_e32 v16, v17, v16
	v_mul_f32_e32 v17, v29, v29
	v_fmac_f32_e32 v17, v28, v28
	v_add_f32_e32 v16, v17, v16
	v_add_f32_e32 v19, v33, v16
	v_mov_b32_e32 v33, v19
	s_nop 1
	v_permlane16_swap_b32_e32 v33, v19
	v_lshl_add_u64 v[16:17], s[36:37], 0, v[102:103]
	v_lshl_add_u64 v[34:35], v[170:171], 1, v[16:17]
	v_cmp_gt_f32_e64 s[0:1], s80, v32
	v_cvt_pk_bf16_f32 v18, v20, v21
	s_waitcnt lgkmcnt(0)
	v_add_f32_e32 v16, v19, v33
	v_mov_b32_e32 v17, v16
	s_nop 1
	v_permlane32_swap_b32_e32 v17, v16
	v_cvt_pk_bf16_f32 v19, v22, v23
	v_cvt_pk_bf16_f32 v20, v30, v31
	v_cvt_pk_bf16_f32 v21, v28, v29
	global_store_dwordx4 v[34:35], v[24:27], off
	global_store_dwordx4 v[34:35], v[18:21], off offset:256
	s_and_saveexec_b64 s[10:11], vcc
	s_cbranch_execz .LBB0_1243
	v_lshl_add_u64 v[18:19], s[12:13], 0, v[106:107]
	v_lshl_add_u64 v[18:19], s[24:25], 2, v[18:19]
	s_lshl_b32 s92, s49, 2
	v_lshl_add_u64 v[18:19], v[18:19], 0, s[92:93]
	s_waitcnt lgkmcnt(0)
	v_add_f32_e32 v16, v16, v17
	global_store_dword v[18:19], v16, off
.LBB0_1243:
	s_or_b64 exec, exec, s[10:11]
	v_mul_f32_e32 v16, 0x4b800000, v32
	v_cndmask_b32_e64 v16, v32, v16, s[0:1]
	v_rsq_f32_e32 v19, v16
	v_lshlrev_b32_e32 v16, 16, v68
	s_waitcnt lgkmcnt(0)
	v_and_b32_e32 v17, 0xffff0000, v68
	v_lshlrev_b32_e32 v18, 16, v69
	v_mul_f32_e32 v20, 0x45800000, v19
	v_cndmask_b32_e64 v19, v19, v20, s[0:1]
	v_mul_f32_e32 v20, v19, v19
	v_and_b32_e32 v19, 0xffff0000, v69
	v_lshlrev_b32_e32 v22, 16, v70
	v_and_b32_e32 v23, 0xffff0000, v70
	v_pk_fma_f32 v[12:13], v[12:13], v[20:21], v[16:17] op_sel_hi:[1,0,1]
	v_pk_fma_f32 v[14:15], v[14:15], v[20:21], v[18:19] op_sel_hi:[1,0,1]
	v_pk_fma_f32 v[18:19], v[8:9], v[20:21], v[22:23] op_sel_hi:[1,0,1]
	v_cvt_pk_bf16_f32 v8, v12, v13
	v_mul_f32_e32 v13, v13, v13
	v_fmac_f32_e32 v13, v12, v12
	v_mul_f32_e32 v12, v15, v15
	v_fmac_f32_e32 v12, v14, v14
	v_lshlrev_b32_e32 v24, 16, v71
	v_and_b32_e32 v25, 0xffff0000, v71
	v_add_f32_e32 v12, v13, v12
	v_mul_f32_e32 v13, v19, v19
	v_pk_fma_f32 v[16:17], v[10:11], v[20:21], v[24:25] op_sel_hi:[1,0,1]
	v_fmac_f32_e32 v13, v18, v18
	v_add_f32_e32 v12, v13, v12
	v_mul_f32_e32 v13, v17, v17
	v_fmac_f32_e32 v13, v16, v16
	v_cvt_pk_bf16_f32 v9, v14, v15
	v_add_f32_e32 v21, v13, v12
	v_lshlrev_b32_e32 v12, 16, v64
	v_and_b32_e32 v13, 0xffff0000, v64
	v_lshlrev_b32_e32 v14, 16, v65
	v_and_b32_e32 v15, 0xffff0000, v65
	v_cvt_pk_bf16_f32 v11, v16, v17
	v_lshlrev_b32_e32 v16, 16, v66
	v_and_b32_e32 v17, 0xffff0000, v66
	v_pk_fma_f32 v[6:7], v[6:7], v[20:21], v[14:15] op_sel_hi:[1,0,1]
	v_pk_fma_f32 v[4:5], v[4:5], v[20:21], v[12:13] op_sel_hi:[1,0,1]
	v_pk_fma_f32 v[14:15], v[0:1], v[20:21], v[16:17] op_sel_hi:[1,0,1]
	v_mul_f32_e32 v0, v5, v5
	v_mul_f32_e32 v1, v7, v7
	v_fmac_f32_e32 v0, v4, v4
	v_fmac_f32_e32 v1, v6, v6
	v_cvt_pk_bf16_f32 v10, v18, v19
	v_lshlrev_b32_e32 v18, 16, v67
	v_and_b32_e32 v19, 0xffff0000, v67
	v_add_f32_e32 v0, v0, v1
	v_mul_f32_e32 v1, v15, v15
	v_pk_fma_f32 v[12:13], v[2:3], v[20:21], v[18:19] op_sel_hi:[1,0,1]
	v_fmac_f32_e32 v1, v14, v14
	v_add_f32_e32 v0, v1, v0
	v_mul_f32_e32 v1, v13, v13
	v_fmac_f32_e32 v1, v12, v12
	v_add_f32_e32 v0, v1, v0
	v_add_f32_e32 v3, v21, v0
	v_mov_b32_e32 v18, v3
	s_nop 1
	v_permlane16_swap_b32_e32 v18, v3
	v_lshl_add_u64 v[0:1], s[36:37], 0, v[96:97]
	v_lshl_add_u64 v[16:17], v[170:171], 1, v[0:1]
	v_cvt_pk_bf16_f32 v2, v4, v5
	v_cvt_pk_bf16_f32 v4, v14, v15
	s_waitcnt lgkmcnt(0)
	v_add_f32_e32 v0, v3, v18
	v_mov_b32_e32 v1, v0
	s_nop 1
	v_permlane32_swap_b32_e32 v1, v0
	v_cvt_pk_bf16_f32 v3, v6, v7
	v_cvt_pk_bf16_f32 v5, v12, v13
	global_store_dwordx4 v[16:17], v[8:11], off
	global_store_dwordx4 v[16:17], v[2:5], off offset:256
	s_and_saveexec_b64 s[0:1], vcc
	s_cbranch_execz .LBB0_1245
	v_lshl_add_u64 v[2:3], s[12:13], 0, v[98:99]
	v_lshl_add_u64 v[2:3], s[24:25], 2, v[2:3]
	s_lshl_b32 s92, s49, 2
	v_lshl_add_u64 v[2:3], v[2:3], 0, s[92:93]
	s_waitcnt lgkmcnt(0)
	v_add_f32_e32 v0, v0, v1
	global_store_dword v[2:3], v0, off
